# speedup vs baseline: 1.0011x; 1.0000x over previous
; template <class ARow, class Epi>
; DI void gemm_tile(const ARow& arow, long a_kstride, const u16* __restrict__ Bt, long ldb, int K, int m0, int n0,
;                   const Epi& epi, char* smem) {
;     ...
;   const int fr = lane & 15, fq = lane >> 4;
;   int foff[2];
; #pragma unroll
;   for (int ks = 0; ks < 2; ++ks) foff[ks] = fr * 128 + ((((4 * ks + fq) ^ ((fr >> 1) & 7))) << 4);
;   f32x4 acc[4][4];
; #pragma unroll
;   for (int a = 0; a < 4; ++a)
; #pragma unroll
;     for (int b = 0; b < 4; ++b) acc[a][b] = (f32x4){0.f, 0.f, 0.f, 0.f};
;   const int KT = K >> 6;
;   GEMM_STAGE(0, 0);
;   asm volatile("s_waitcnt vmcnt(0)" ::: "memory");
;   __syncthreads();
;   for (int kt = 0; kt < KT; ++kt) {
;     const int cur = kt & 1;
;     if (kt + 1 < KT) GEMM_STAGE(cur ^ 1, kt + 1);
;     const char* sa = smem + cur * 32768 + wm * 64 * 128;
;     const char* sb = smem + cur * 32768 + 16384 + wn * 64 * 128;
; #pragma unroll
;     for (int ks = 0; ks < 2; ++ks) {
;       bf16x8 wf[4], af[4];
; #pragma unroll
;       for (int j = 0; j < 4; ++j) {
;         wf[j] = *(const bf16x8*)(sb + j * 2048 + foff[ks]);
;         af[j] = *(const bf16x8*)(sa + j * 2048 + foff[ks]);
;       }
; #pragma unroll
;       for (int ni = 0; ni < 4; ++ni)
; #pragma unroll
;         for (int mi = 0; mi < 4; ++mi) acc[ni][mi] = __builtin_amdgcn_mfma_f32_16x16x32_bf16(wf[ni], af[mi], acc[ni][mi], 0, 0, 0);
;     }
;     asm volatile("s_waitcnt vmcnt(0)" ::: "memory");
;     __syncthreads();
;   }
.LBB0_217:
	s_and_b32 s6, s1, 0x8000
	v_add_u32_e32 v116, s6, v89
	v_or_b32_e32 v117, s6, v90
	v_add_u32_e32 v118, v117, v88
	v_add_u32_e32 v112, v116, v88
	ds_read_b128 v[92:95], v118 offset:16384
	ds_read_b128 v[96:99], v112
	ds_read_b128 v[100:103], v118 offset:18432
	ds_read_b128 v[104:107], v112 offset:2048
	ds_read_b128 v[108:111], v112 offset:4096
	ds_read_b128 v[112:115], v112 offset:6144
	s_xor_b32 s7, s6, 0x8000
	v_add_u32_e32 v176, s7, v91
	s_nop 0
	v_readfirstlane_b32 s6, v176
	v_add_u32_e32 v177, 0x4000, v176
	v_lshl_add_u64 v[160:161], v[66:67], 0, s[4:5]
	v_add_u32_e32 v178, 0x400, v176
	v_readfirstlane_b32 s7, v177
	s_mov_b32 m0, s6
	v_lshl_add_u64 v[162:163], v[68:69], 0, s[4:5]
	v_add_u32_e32 v179, 0x4400, v176
	v_readfirstlane_b32 s8, v178
	global_load_lds_dwordx4 v[160:161], off
	s_mov_b32 m0, s7
	v_lshl_add_u64 v[164:165], v[70:71], 0, s[4:5]
	v_add_u32_e32 v181, 0x800, v176
	v_readfirstlane_b32 s9, v179
	global_load_lds_dwordx4 v[162:163], off
	s_mov_b32 m0, s8
	v_lshl_add_u64 v[166:167], v[72:73], 0, s[4:5]
	v_add_u32_e32 v182, 0x4800, v176
	v_readfirstlane_b32 s10, v181
	global_load_lds_dwordx4 v[164:165], off
	s_mov_b32 m0, s9
	v_lshl_add_u64 v[168:169], v[74:75], 0, s[4:5]
	v_add_u32_e32 v183, 0xc00, v176
	v_readfirstlane_b32 s11, v182
	global_load_lds_dwordx4 v[166:167], off
	s_mov_b32 m0, s10
	v_lshl_add_u64 v[170:171], v[76:77], 0, s[4:5]
	v_add_u32_e32 v176, 0x4c00, v176
	v_readfirstlane_b32 s12, v183
	global_load_lds_dwordx4 v[168:169], off
	s_mov_b32 m0, s11
	v_lshl_add_u64 v[172:173], v[78:79], 0, s[4:5]
	v_readfirstlane_b32 s13, v176
	global_load_lds_dwordx4 v[170:171], off
	s_mov_b32 m0, s12
	v_lshl_add_u64 v[174:175], v[80:81], 0, s[4:5]
	global_load_lds_dwordx4 v[172:173], off
	s_mov_b32 m0, s13
	global_load_lds_dwordx4 v[174:175], off
	s_waitcnt lgkmcnt(0)
	v_mfma_f32_16x16x32_bf16 v[60:63], v[92:95], v[96:99], v[60:63]
	v_add_u32_e32 v117, v117, v87
	v_add_u32_e32 v116, v116, v87
	s_add_i32 s1, s1, 0x8000
	v_mfma_f32_16x16x32_bf16 v[56:59], v[92:95], v[104:107], v[56:59]
	s_add_u32 s4, s4, 0x80
	s_addc_u32 s5, s5, 0
	s_cmpk_eq_i32 s4, 0x780
	v_mfma_f32_16x16x32_bf16 v[48:51], v[92:95], v[108:111], v[48:51]
	v_mfma_f32_16x16x32_bf16 v[40:43], v[92:95], v[112:115], v[40:43]
	v_mfma_f32_16x16x32_bf16 v[36:39], v[100:103], v[96:99], v[36:39]
	v_mfma_f32_16x16x32_bf16 v[32:35], v[100:103], v[104:107], v[32:35]
	v_mfma_f32_16x16x32_bf16 v[28:31], v[100:103], v[108:111], v[28:31]
	v_mfma_f32_16x16x32_bf16 v[24:27], v[100:103], v[112:115], v[24:27]
	ds_read_b128 v[92:95], v118 offset:20480
	ds_read_b128 v[100:103], v118 offset:22528
	s_waitcnt lgkmcnt(1)
	v_mfma_f32_16x16x32_bf16 v[20:23], v[92:95], v[96:99], v[20:23]
	v_mfma_f32_16x16x32_bf16 v[16:19], v[92:95], v[104:107], v[16:19]
	v_mfma_f32_16x16x32_bf16 v[12:15], v[92:95], v[108:111], v[12:15]
	v_mfma_f32_16x16x32_bf16 v[8:11], v[92:95], v[112:115], v[8:11]
	ds_read_b128 v[92:95], v117 offset:16384
	s_waitcnt lgkmcnt(1)
	v_mfma_f32_16x16x32_bf16 v[4:7], v[100:103], v[96:99], v[4:7]
	v_mfma_f32_16x16x32_bf16 v[0:3], v[100:103], v[104:107], v[0:3]
	v_mfma_f32_16x16x32_bf16 v[52:55], v[100:103], v[108:111], v[52:55]
	v_mfma_f32_16x16x32_bf16 v[44:47], v[100:103], v[112:115], v[44:47]
	ds_read_b128 v[96:99], v116
	ds_read_b128 v[100:103], v117 offset:18432
	ds_read_b128 v[104:107], v116 offset:2048
	ds_read_b128 v[108:111], v116 offset:4096
	ds_read_b128 v[112:115], v116 offset:6144
	s_waitcnt lgkmcnt(4)
	v_mfma_f32_16x16x32_bf16 v[60:63], v[92:95], v[96:99], v[60:63]
	s_waitcnt lgkmcnt(2)
	v_mfma_f32_16x16x32_bf16 v[56:59], v[92:95], v[104:107], v[56:59]
	s_waitcnt lgkmcnt(1)
	v_mfma_f32_16x16x32_bf16 v[48:51], v[92:95], v[108:111], v[48:51]
	s_waitcnt lgkmcnt(0)
	v_mfma_f32_16x16x32_bf16 v[40:43], v[92:95], v[112:115], v[40:43]
	v_mfma_f32_16x16x32_bf16 v[36:39], v[100:103], v[96:99], v[36:39]
	v_mfma_f32_16x16x32_bf16 v[32:35], v[100:103], v[104:107], v[32:35]
	v_mfma_f32_16x16x32_bf16 v[28:31], v[100:103], v[108:111], v[28:31]
	v_mfma_f32_16x16x32_bf16 v[24:27], v[100:103], v[112:115], v[24:27]
	ds_read_b128 v[92:95], v117 offset:20480
	ds_read_b128 v[100:103], v117 offset:22528
	s_waitcnt lgkmcnt(0)
	s_waitcnt vmcnt(0)
	s_waitcnt vmcnt(0) lgkmcnt(0)
	v_mfma_f32_16x16x32_bf16 v[20:23], v[92:95], v[96:99], v[20:23]
	s_barrier
	v_mfma_f32_16x16x32_bf16 v[16:19], v[92:95], v[104:107], v[16:19]
	v_mfma_f32_16x16x32_bf16 v[12:15], v[92:95], v[108:111], v[12:15]
	v_mfma_f32_16x16x32_bf16 v[8:11], v[92:95], v[112:115], v[8:11]
	v_mfma_f32_16x16x32_bf16 v[4:7], v[100:103], v[96:99], v[4:7]
	v_mfma_f32_16x16x32_bf16 v[0:3], v[100:103], v[104:107], v[0:3]
	v_mfma_f32_16x16x32_bf16 v[52:55], v[100:103], v[108:111], v[52:55]
	v_mfma_f32_16x16x32_bf16 v[44:47], v[100:103], v[112:115], v[44:47]
	s_cbranch_scc0 .LBB0_217
; template <class ARow, class Epi>
; DI void gemm_tile(const ARow& arow, long a_kstride, const u16* __restrict__ Bt, long ldb, int K, int m0, int n0,
;                   const Epi& epi, char* smem) {
;     ...
;     for (int ks = 0; ks < 2; ++ks) {
;       bf16x8 wf[4], af[4];
; #pragma unroll
;       for (int j = 0; j < 4; ++j) {
;         wf[j] = *(const bf16x8*)(sb + j * 2048 + foff[ks]);
;         af[j] = *(const bf16x8*)(sa + j * 2048 + foff[ks]);
;       }
; #pragma unroll
;       for (int ni = 0; ni < 4; ++ni)
; #pragma unroll
;         for (int mi = 0; mi < 4; ++mi) acc[ni][mi] = __builtin_amdgcn_mfma_f32_16x16x32_bf16(wf[ni], af[mi], acc[ni][mi], 0, 0, 0);
;     }
;     asm volatile("s_waitcnt vmcnt(0)" ::: "memory");
;     __syncthreads();
;   }
;     ...
;   const int nh = n0 + wn * 64;
;   if (epi.packed(nh)) {
; #pragma unroll
;     for (int mi = 0; mi < 4; ++mi) {
;       const int m = m0 + wm * 64 + mi * 16 + fr;
	v_add_u32_e32 v91, v90, v88
	ds_read_b128 v[66:69], v91 offset:49152
	v_add_u32_e32 v88, v89, v88
	ds_read_b128 v[70:73], v88 offset:32768
	ds_read_b128 v[74:77], v88 offset:34816
	ds_read_b128 v[78:81], v88 offset:36864
	ds_read_b128 v[92:95], v88 offset:38912
	v_add_u32_e32 v116, v90, v87
	s_waitcnt lgkmcnt(3)
	v_mfma_f32_16x16x32_bf16 v[60:63], v[66:69], v[70:73], v[60:63]
	s_waitcnt lgkmcnt(2)
	v_mfma_f32_16x16x32_bf16 v[56:59], v[66:69], v[74:77], v[56:59]
	s_waitcnt lgkmcnt(1)
	v_mfma_f32_16x16x32_bf16 v[48:51], v[66:69], v[78:81], v[48:51]
	s_waitcnt lgkmcnt(0)
	v_mfma_f32_16x16x32_bf16 v[40:43], v[66:69], v[92:95], v[40:43]
	ds_read_b128 v[66:69], v91 offset:51200
	s_waitcnt lgkmcnt(0)
	v_mfma_f32_16x16x32_bf16 v[36:39], v[66:69], v[70:73], v[36:39]
	v_mfma_f32_16x16x32_bf16 v[32:35], v[66:69], v[74:77], v[32:35]
	v_mfma_f32_16x16x32_bf16 v[96:99], v[66:69], v[78:81], v[28:31]
	v_mfma_f32_16x16x32_bf16 v[66:69], v[66:69], v[92:95], v[24:27]
	s_nop 2
	ds_read_b128 v[24:27], v91 offset:53248
	s_waitcnt lgkmcnt(0)
	v_mfma_f32_16x16x32_bf16 v[104:107], v[24:27], v[92:95], v[8:11]
	s_nop 2
	ds_read_b128 v[8:11], v91 offset:55296
	v_mfma_f32_16x16x32_bf16 v[20:23], v[24:27], v[70:73], v[20:23]
	s_waitcnt lgkmcnt(0)
	v_mfma_f32_16x16x32_bf16 v[70:73], v[8:11], v[70:73], v[4:7]
	s_nop 2
	ds_read_b128 v[4:7], v116 offset:49152
	v_mfma_f32_16x16x32_bf16 v[100:103], v[24:27], v[78:81], v[12:15]
	s_nop 2
	v_add_u32_e32 v12, v89, v87
	v_mfma_f32_16x16x32_bf16 v[16:19], v[24:27], v[74:77], v[16:19]
	ds_read_b128 v[88:91], v12 offset:32768
	ds_read_b128 v[108:111], v12 offset:36864
	ds_read_b128 v[112:115], v12 offset:38912
	v_mfma_f32_16x16x32_bf16 v[0:3], v[8:11], v[74:77], v[0:3]
	v_mfma_f32_16x16x32_bf16 v[74:77], v[8:11], v[78:81], v[52:55]
	v_mfma_f32_16x16x32_bf16 v[78:81], v[8:11], v[92:95], v[44:47]
	ds_read_b128 v[92:95], v12 offset:34816
	s_waitcnt lgkmcnt(3)
	v_mfma_f32_16x16x32_bf16 v[60:63], v[4:7], v[88:91], v[60:63]
	s_waitcnt lgkmcnt(0)
	v_mfma_f32_16x16x32_bf16 v[44:47], v[4:7], v[92:95], v[56:59]
	v_mfma_f32_16x16x32_bf16 v[28:31], v[4:7], v[108:111], v[48:51]
	v_mfma_f32_16x16x32_bf16 v[12:15], v[4:7], v[112:115], v[40:43]
	ds_read_b128 v[4:7], v116 offset:51200
	s_waitcnt lgkmcnt(0)
	v_mfma_f32_16x16x32_bf16 v[56:59], v[4:7], v[88:91], v[36:39]
	v_mfma_f32_16x16x32_bf16 v[40:43], v[4:7], v[92:95], v[32:35]
	v_mfma_f32_16x16x32_bf16 v[24:27], v[4:7], v[108:111], v[96:99]
	v_mfma_f32_16x16x32_bf16 v[8:11], v[4:7], v[112:115], v[66:69]
	ds_read_b128 v[4:7], v116 offset:53248
	s_nop 0
	ds_read_b128 v[96:99], v116 offset:55296
	s_waitcnt lgkmcnt(0)
	s_waitcnt vmcnt(0)
	s_waitcnt lgkmcnt(0)
	v_mfma_f32_16x16x32_bf16 v[32:35], v[96:99], v[92:95], v[0:3]
	s_nop 2
	v_or_b32_e32 v0, s0, v64
	v_lshl_or_b32 v66, v85, 6, s42
	v_cmp_lt_i32_e32 vcc, s33, v66
	v_mfma_f32_16x16x32_bf16 v[52:55], v[4:7], v[88:91], v[20:23]
	s_barrier
	v_mfma_f32_16x16x32_bf16 v[36:39], v[4:7], v[92:95], v[16:19]
	v_mfma_f32_16x16x32_bf16 v[20:23], v[4:7], v[108:111], v[100:103]
	v_mfma_f32_16x16x32_bf16 v[4:7], v[4:7], v[112:115], v[104:107]
	v_mfma_f32_16x16x32_bf16 v[48:51], v[96:99], v[88:91], v[70:73]
	v_mfma_f32_16x16x32_bf16 v[16:19], v[96:99], v[108:111], v[74:77]
	s_nop 1
	v_lshlrev_b32_e32 v70, 2, v84
	v_or_b32_e32 v64, v66, v70
	v_lshl_add_u32 v74, v86, 6, v0
	v_mfma_f32_16x16x32_bf16 v[0:3], v[96:99], v[112:115], v[78:81]
	s_nop 7
	v_readfirstlane_b32 s99, v66
	s_cmpk_lt_u32 s99, 0x400
	s_cbranch_scc0 .Lfe_A_not_q
; DI unsigned pack2(float a, float b) { v2f f = {a, b}; return __builtin_bit_cast(unsigned, __builtin_convertvector(f, v2bf)); }
; DI float silu_f(float v) { return v / (1.f + fexp(-v)); }
;   DI u32x2 pack(int, int, float a, float b, float c, float d, float&) const { u32x2 v; v.x = pack2(a, b); v.y = pack2(c, d); return v; }
; template <class ARow, class Epi>
; DI void gemm_tile(const ARow& arow, long a_kstride, const u16* __restrict__ Bt, long ldb, int K, int m0, int n0,
;                   const Epi& epi, char* smem) {
;     ...
;       for (int ni = 0; ni < 4; ++ni) pk[ni] = epi.pack(m, nh + ni * 16 + fq * 4, acc[ni][mi][0], acc[ni][mi][1], acc[ni][mi][2], acc[ni][mi][3], ss);
;       epi.finish16(m, nh, ss);
;       u16* rp = epi.rowp(m) + nh;
; #pragma unroll
;       for (int pp = 0; pp < 2; ++pp) {
;         u32x2 a = pk[2 * pp], b = pk[2 * pp + 1];
;         const u32x2 rx = __builtin_amdgcn_permlane16_swap(a.x, b.x, false, false);
;         const u32x2 ry = __builtin_amdgcn_permlane16_swap(a.y, b.y, false, false);
;         const int nst = (fq & 1) ? ((2 * pp + 1) * 16 + (fq - 1) * 4) : ((2 * pp) * 16 + fq * 4);
;         *(u32x4*)(rp + nst) = (u32x4){rx[0], ry[0], rx[1], ry[1]};
;       }
;   DI u32x2 pack(int m, int n, float a, float b, float c, float d, float& ss) const {
;     if (n < q_end) { a *= qscale; b *= qscale; c *= qscale; d *= qscale; }
;     else if (n >= z_start) { a = silu_f(a); b = silu_f(b); c = silu_f(c); d = silu_f(d); }
;     ss += a * a + b * b + c * c + d * d;
;     u32x2 v; v.x = pack2(a, b); v.y = pack2(c, d);
;     return v;
	s_load_dwordx2 s[100:101], s[56:57], 0x130
	v_and_b32_e32 v152, 1, v84
	v_mul_u32_u24_e32 v152, 12, v152
	v_lshl_add_u32 v152, v84, 2, v152
	v_add_u32_e32 v152, v152, v66
	v_mul_u32_u24_e32 v153, 0xe00, v74
	v_add_u32_e32 v152, v152, v153
	v_lshlrev_b32_e32 v152, 1, v152
	v_add_u32_e32 v153, 0x1c000, v152
	v_add_u32_e32 v154, 0x38000, v152
	v_add_u32_e32 v155, 0x54000, v152
	s_mov_b32 s98, 0x3e38aa3b
	s_nop 3
	v_pk_mul_f32 v[60:61], v[60:61], s[98:99] op_sel_hi:[1,0]
	v_pk_mul_f32 v[62:63], v[62:63], s[98:99] op_sel_hi:[1,0]
	v_pk_mul_f32 v[56:57], v[56:57], s[98:99] op_sel_hi:[1,0]
	v_pk_mul_f32 v[58:59], v[58:59], s[98:99] op_sel_hi:[1,0]
	v_pk_mul_f32 v[52:53], v[52:53], s[98:99] op_sel_hi:[1,0]
	v_pk_mul_f32 v[54:55], v[54:55], s[98:99] op_sel_hi:[1,0]
	v_pk_mul_f32 v[48:49], v[48:49], s[98:99] op_sel_hi:[1,0]
	v_pk_mul_f32 v[50:51], v[50:51], s[98:99] op_sel_hi:[1,0]
	v_cvt_pk_bf16_f32 v120, v60, v61
	v_cvt_pk_bf16_f32 v121, v62, v63
	v_cvt_pk_bf16_f32 v122, v56, v57
	v_cvt_pk_bf16_f32 v123, v58, v59
	v_cvt_pk_bf16_f32 v124, v52, v53
	v_cvt_pk_bf16_f32 v125, v54, v55
	v_cvt_pk_bf16_f32 v126, v48, v49
	v_cvt_pk_bf16_f32 v127, v50, v51
	s_nop 1
	v_permlane16_swap_b32_e32 v120, v122
	v_permlane16_swap_b32_e32 v121, v123
	v_permlane16_swap_b32_e32 v124, v126
	v_permlane16_swap_b32_e32 v125, v127
	s_waitcnt lgkmcnt(0)
	global_store_dwordx4 v152, v[120:123], s[100:101]
	global_store_dwordx4 v152, v[124:127], s[100:101] offset:64
	v_pk_mul_f32 v[44:45], v[44:45], s[98:99] op_sel_hi:[1,0]
	v_pk_mul_f32 v[46:47], v[46:47], s[98:99] op_sel_hi:[1,0]
	v_pk_mul_f32 v[40:41], v[40:41], s[98:99] op_sel_hi:[1,0]
	v_pk_mul_f32 v[42:43], v[42:43], s[98:99] op_sel_hi:[1,0]
	v_pk_mul_f32 v[36:37], v[36:37], s[98:99] op_sel_hi:[1,0]
	v_pk_mul_f32 v[38:39], v[38:39], s[98:99] op_sel_hi:[1,0]
	v_pk_mul_f32 v[32:33], v[32:33], s[98:99] op_sel_hi:[1,0]
	v_pk_mul_f32 v[34:35], v[34:35], s[98:99] op_sel_hi:[1,0]
	v_cvt_pk_bf16_f32 v128, v44, v45
	v_cvt_pk_bf16_f32 v129, v46, v47
	v_cvt_pk_bf16_f32 v130, v40, v41
	v_cvt_pk_bf16_f32 v131, v42, v43
	v_cvt_pk_bf16_f32 v132, v36, v37
	v_cvt_pk_bf16_f32 v133, v38, v39
	v_cvt_pk_bf16_f32 v134, v32, v33
	v_cvt_pk_bf16_f32 v135, v34, v35
	s_nop 1
	v_permlane16_swap_b32_e32 v128, v130
	v_permlane16_swap_b32_e32 v129, v131
	v_permlane16_swap_b32_e32 v132, v134
	v_permlane16_swap_b32_e32 v133, v135
	global_store_dwordx4 v153, v[128:131], s[100:101]
	global_store_dwordx4 v153, v[132:135], s[100:101] offset:64
	v_pk_mul_f32 v[28:29], v[28:29], s[98:99] op_sel_hi:[1,0]
	v_pk_mul_f32 v[30:31], v[30:31], s[98:99] op_sel_hi:[1,0]
	v_pk_mul_f32 v[24:25], v[24:25], s[98:99] op_sel_hi:[1,0]
	v_pk_mul_f32 v[26:27], v[26:27], s[98:99] op_sel_hi:[1,0]
	v_pk_mul_f32 v[20:21], v[20:21], s[98:99] op_sel_hi:[1,0]
	v_pk_mul_f32 v[22:23], v[22:23], s[98:99] op_sel_hi:[1,0]
	v_pk_mul_f32 v[16:17], v[16:17], s[98:99] op_sel_hi:[1,0]
	v_pk_mul_f32 v[18:19], v[18:19], s[98:99] op_sel_hi:[1,0]
	v_cvt_pk_bf16_f32 v136, v28, v29
	v_cvt_pk_bf16_f32 v137, v30, v31
	v_cvt_pk_bf16_f32 v138, v24, v25
	v_cvt_pk_bf16_f32 v139, v26, v27
	v_cvt_pk_bf16_f32 v140, v20, v21
	v_cvt_pk_bf16_f32 v141, v22, v23
	v_cvt_pk_bf16_f32 v142, v16, v17
	v_cvt_pk_bf16_f32 v143, v18, v19
	s_nop 1
	v_permlane16_swap_b32_e32 v136, v138
	v_permlane16_swap_b32_e32 v137, v139
	v_permlane16_swap_b32_e32 v140, v142
	v_permlane16_swap_b32_e32 v141, v143
	global_store_dwordx4 v154, v[136:139], s[100:101]
	global_store_dwordx4 v154, v[140:143], s[100:101] offset:64
	v_pk_mul_f32 v[12:13], v[12:13], s[98:99] op_sel_hi:[1,0]
	v_pk_mul_f32 v[14:15], v[14:15], s[98:99] op_sel_hi:[1,0]
	v_pk_mul_f32 v[8:9], v[8:9], s[98:99] op_sel_hi:[1,0]
	v_pk_mul_f32 v[10:11], v[10:11], s[98:99] op_sel_hi:[1,0]
	v_pk_mul_f32 v[4:5], v[4:5], s[98:99] op_sel_hi:[1,0]
	v_pk_mul_f32 v[6:7], v[6:7], s[98:99] op_sel_hi:[1,0]
	v_pk_mul_f32 v[0:1], v[0:1], s[98:99] op_sel_hi:[1,0]
	v_pk_mul_f32 v[2:3], v[2:3], s[98:99] op_sel_hi:[1,0]
	v_cvt_pk_bf16_f32 v144, v12, v13
	v_cvt_pk_bf16_f32 v145, v14, v15
	v_cvt_pk_bf16_f32 v146, v8, v9
	v_cvt_pk_bf16_f32 v147, v10, v11
	v_cvt_pk_bf16_f32 v148, v4, v5
	v_cvt_pk_bf16_f32 v149, v6, v7
	v_cvt_pk_bf16_f32 v150, v0, v1
	v_cvt_pk_bf16_f32 v151, v2, v3
	s_nop 1
	v_permlane16_swap_b32_e32 v144, v146
	v_permlane16_swap_b32_e32 v145, v147
	v_permlane16_swap_b32_e32 v148, v150
	v_permlane16_swap_b32_e32 v149, v151
	global_store_dwordx4 v155, v[144:147], s[100:101]
	global_store_dwordx4 v155, v[148:151], s[100:101] offset:64
	s_branch .Lfe_join_A

; template <class ARow, class Epi>
; DI void gemm_tile(const ARow& arow, long a_kstride, const u16* __restrict__ Bt, long ldb, int K, int m0, int n0,
;                   const Epi& epi, char* smem) {
;     ...
;   const int fr = lane & 15, fq = lane >> 4;
;   int foff[2];
; #pragma unroll
;   for (int ks = 0; ks < 2; ++ks) foff[ks] = fr * 128 + ((((4 * ks + fq) ^ ((fr >> 1) & 7))) << 4);
;   f32x4 acc[4][4];
; #pragma unroll
;   for (int a = 0; a < 4; ++a)
; #pragma unroll
;     for (int b = 0; b < 4; ++b) acc[a][b] = (f32x4){0.f, 0.f, 0.f, 0.f};
;   const int KT = K >> 6;
;   GEMM_STAGE(0, 0);
;   asm volatile("s_waitcnt vmcnt(0)" ::: "memory");
;   __syncthreads();
;   for (int kt = 0; kt < KT; ++kt) {
;     const int cur = kt & 1;
;     if (kt + 1 < KT) GEMM_STAGE(cur ^ 1, kt + 1);
;     const char* sa = smem + cur * 32768 + wm * 64 * 128;
;     const char* sb = smem + cur * 32768 + 16384 + wn * 64 * 128;
; #pragma unroll
;     for (int ks = 0; ks < 2; ++ks) {
;       bf16x8 wf[4], af[4];
; #pragma unroll
;       for (int j = 0; j < 4; ++j) {
;         wf[j] = *(const bf16x8*)(sb + j * 2048 + foff[ks]);
;         af[j] = *(const bf16x8*)(sa + j * 2048 + foff[ks]);
;       }
; #pragma unroll
;       for (int ni = 0; ni < 4; ++ni)
; #pragma unroll
;         for (int mi = 0; mi < 4; ++mi) acc[ni][mi] = __builtin_amdgcn_mfma_f32_16x16x32_bf16(wf[ni], af[mi], acc[ni][mi], 0, 0, 0);
;     }
;     asm volatile("s_waitcnt vmcnt(0)" ::: "memory");
;     __syncthreads();
;   }
.LBB0_1045:
	s_and_b32 s20, s19, 0x8000
	v_add_u32_e32 v91, s20, v89
	v_or_b32_e32 v116, s20, v90
	v_add_u32_e32 v117, v116, v87
	v_add_u32_e32 v112, v91, v87
	ds_read_b128 v[92:95], v117 offset:16384
	ds_read_b128 v[96:99], v112
	ds_read_b128 v[100:103], v117 offset:18432
	ds_read_b128 v[104:107], v112 offset:2048
	ds_read_b128 v[108:111], v112 offset:4096
	ds_read_b128 v[112:115], v112 offset:6144
	s_xor_b32 s21, s20, 0x8000
	v_add_u32_e32 v176, s21, v88
	s_nop 0
	v_readfirstlane_b32 s20, v176
	v_add_u32_e32 v177, 0x4000, v176
	v_lshl_add_u64 v[160:161], v[66:67], 0, s[16:17]
	v_add_u32_e32 v178, 0x400, v176
	v_readfirstlane_b32 s21, v177
	s_mov_b32 m0, s20
	v_lshl_add_u64 v[162:163], v[68:69], 0, s[16:17]
	v_add_u32_e32 v179, 0x4400, v176
	v_readfirstlane_b32 s22, v178
	global_load_lds_dwordx4 v[160:161], off
	s_mov_b32 m0, s21
	v_lshl_add_u64 v[164:165], v[70:71], 0, s[16:17]
	v_add_u32_e32 v181, 0x800, v176
	v_readfirstlane_b32 s23, v179
	global_load_lds_dwordx4 v[162:163], off
	s_mov_b32 m0, s22
	v_lshl_add_u64 v[166:167], v[72:73], 0, s[16:17]
	v_add_u32_e32 v182, 0x4800, v176
	v_readfirstlane_b32 s24, v181
	global_load_lds_dwordx4 v[164:165], off
	s_mov_b32 m0, s23
	v_lshl_add_u64 v[168:169], v[74:75], 0, s[16:17]
	v_add_u32_e32 v183, 0xc00, v176
	v_readfirstlane_b32 s25, v182
	global_load_lds_dwordx4 v[166:167], off
	s_mov_b32 m0, s24
	v_lshl_add_u64 v[170:171], v[76:77], 0, s[16:17]
	v_add_u32_e32 v176, 0x4c00, v176
	v_readfirstlane_b32 s26, v183
	global_load_lds_dwordx4 v[168:169], off
	s_mov_b32 m0, s25
	v_lshl_add_u64 v[172:173], v[78:79], 0, s[16:17]
	v_readfirstlane_b32 s27, v176
	global_load_lds_dwordx4 v[170:171], off
	s_mov_b32 m0, s26
	v_lshl_add_u64 v[174:175], v[80:81], 0, s[16:17]
	global_load_lds_dwordx4 v[172:173], off
	s_mov_b32 m0, s27
	global_load_lds_dwordx4 v[174:175], off
	s_waitcnt lgkmcnt(0)
	v_mfma_f32_16x16x32_bf16 v[60:63], v[92:95], v[96:99], v[60:63]
	v_add_u32_e32 v116, v116, v86
	v_add_u32_e32 v91, v91, v86
	s_add_i32 s19, s19, 0x8000
	v_mfma_f32_16x16x32_bf16 v[56:59], v[92:95], v[104:107], v[56:59]
	s_add_u32 s16, s16, 0x80
	s_addc_u32 s17, s17, 0
	s_cmpk_lg_i32 s16, 0x780
	v_mfma_f32_16x16x32_bf16 v[52:55], v[92:95], v[108:111], v[52:55]
	v_mfma_f32_16x16x32_bf16 v[48:51], v[92:95], v[112:115], v[48:51]
	v_mfma_f32_16x16x32_bf16 v[44:47], v[100:103], v[96:99], v[44:47]
	v_mfma_f32_16x16x32_bf16 v[40:43], v[100:103], v[104:107], v[40:43]
	v_mfma_f32_16x16x32_bf16 v[36:39], v[100:103], v[108:111], v[36:39]
	v_mfma_f32_16x16x32_bf16 v[16:19], v[100:103], v[112:115], v[16:19]
	ds_read_b128 v[92:95], v117 offset:20480
	ds_read_b128 v[100:103], v117 offset:22528
	s_waitcnt lgkmcnt(1)
	v_mfma_f32_16x16x32_bf16 v[32:35], v[92:95], v[96:99], v[32:35]
	v_mfma_f32_16x16x32_bf16 v[12:15], v[92:95], v[104:107], v[12:15]
	v_mfma_f32_16x16x32_bf16 v[8:11], v[92:95], v[108:111], v[8:11]
	v_mfma_f32_16x16x32_bf16 v[4:7], v[92:95], v[112:115], v[4:7]
	ds_read_b128 v[92:95], v116 offset:16384
	s_waitcnt lgkmcnt(1)
	v_mfma_f32_16x16x32_bf16 v[24:27], v[100:103], v[96:99], v[24:27]
	v_mfma_f32_16x16x32_bf16 v[0:3], v[100:103], v[104:107], v[0:3]
	v_mfma_f32_16x16x32_bf16 v[28:31], v[100:103], v[108:111], v[28:31]
	v_mfma_f32_16x16x32_bf16 v[20:23], v[100:103], v[112:115], v[20:23]
	ds_read_b128 v[96:99], v91
	ds_read_b128 v[100:103], v116 offset:18432
	ds_read_b128 v[104:107], v91 offset:2048
	ds_read_b128 v[108:111], v91 offset:4096
	ds_read_b128 v[112:115], v91 offset:6144
	s_waitcnt lgkmcnt(4)
	v_mfma_f32_16x16x32_bf16 v[60:63], v[92:95], v[96:99], v[60:63]
	s_waitcnt lgkmcnt(2)
	v_mfma_f32_16x16x32_bf16 v[56:59], v[92:95], v[104:107], v[56:59]
	s_waitcnt lgkmcnt(1)
	v_mfma_f32_16x16x32_bf16 v[52:55], v[92:95], v[108:111], v[52:55]
	s_waitcnt lgkmcnt(0)
	v_mfma_f32_16x16x32_bf16 v[48:51], v[92:95], v[112:115], v[48:51]
	v_mfma_f32_16x16x32_bf16 v[44:47], v[100:103], v[96:99], v[44:47]
	v_mfma_f32_16x16x32_bf16 v[40:43], v[100:103], v[104:107], v[40:43]
	v_mfma_f32_16x16x32_bf16 v[36:39], v[100:103], v[108:111], v[36:39]
	v_mfma_f32_16x16x32_bf16 v[16:19], v[100:103], v[112:115], v[16:19]
	ds_read_b128 v[92:95], v116 offset:20480
	ds_read_b128 v[100:103], v116 offset:22528
	s_waitcnt lgkmcnt(0)
	s_waitcnt vmcnt(0)
	s_waitcnt vmcnt(0) lgkmcnt(0)
	v_mfma_f32_16x16x32_bf16 v[32:35], v[92:95], v[96:99], v[32:35]
	s_barrier
	v_mfma_f32_16x16x32_bf16 v[12:15], v[92:95], v[104:107], v[12:15]
	v_mfma_f32_16x16x32_bf16 v[8:11], v[92:95], v[108:111], v[8:11]
	v_mfma_f32_16x16x32_bf16 v[4:7], v[92:95], v[112:115], v[4:7]
	v_mfma_f32_16x16x32_bf16 v[24:27], v[100:103], v[96:99], v[24:27]
	v_mfma_f32_16x16x32_bf16 v[0:3], v[100:103], v[104:107], v[0:3]
	v_mfma_f32_16x16x32_bf16 v[28:31], v[100:103], v[108:111], v[28:31]
	v_mfma_f32_16x16x32_bf16 v[20:23], v[100:103], v[112:115], v[20:23]
	s_cbranch_scc1 .LBB0_1045
	v_add_u32_e32 v91, v90, v87
	ds_read_b128 v[66:69], v91 offset:49152
	v_add_u32_e32 v87, v89, v87
	ds_read_b128 v[70:73], v87 offset:32768
	ds_read_b128 v[74:77], v87 offset:34816
	ds_read_b128 v[78:81], v87 offset:36864
	ds_read_b128 v[92:95], v87 offset:38912
	v_add_u32_e32 v120, v89, v86
	v_add_u32_e32 v90, v90, v86
	v_or_b32_e32 v64, s1, v64
	s_waitcnt lgkmcnt(3)
	v_mfma_f32_16x16x32_bf16 v[60:63], v[66:69], v[70:73], v[60:63]
	s_waitcnt lgkmcnt(2)
	v_mfma_f32_16x16x32_bf16 v[56:59], v[66:69], v[74:77], v[56:59]
	s_waitcnt lgkmcnt(1)
	v_mfma_f32_16x16x32_bf16 v[52:55], v[66:69], v[78:81], v[52:55]
	s_waitcnt lgkmcnt(0)
	v_mfma_f32_16x16x32_bf16 v[48:51], v[66:69], v[92:95], v[48:51]
	ds_read_b128 v[66:69], v91 offset:51200
	ds_read_b128 v[86:89], v120 offset:38912
	ds_read_b128 v[96:99], v120 offset:36864
	ds_read_b128 v[100:103], v91 offset:55296
	ds_read_b128 v[104:107], v91 offset:53248
	ds_read_b128 v[108:111], v90 offset:55296
	ds_read_b128 v[112:115], v90 offset:53248
	ds_read_b128 v[116:119], v120 offset:34816
	ds_read_b128 v[120:123], v120 offset:32768
	ds_read_b128 v[124:127], v90 offset:51200
	ds_read_b128 v[128:131], v90 offset:49152
	s_waitcnt lgkmcnt(6)
	v_mfma_f32_16x16x32_bf16 v[32:35], v[104:107], v[70:73], v[32:35]
	s_waitcnt lgkmcnt(0)
	s_waitcnt vmcnt(0)
	s_waitcnt lgkmcnt(0)
	s_barrier
;   DI u32x2 pack(int, int, float a, float b, float c, float d, float&) const { u32x2 v; v.x = pack2(a, b); v.y = pack2(c, d); return v; }
; template <class ARow, class Epi>
; DI void gemm_tile(const ARow& arow, long a_kstride, const u16* __restrict__ Bt, long ldb, int K, int m0, int n0,
;                   const Epi& epi, char* smem) {
;     ...
;     for (int ks = 0; ks < 2; ++ks) {
;       bf16x8 wf[4], af[4];
; #pragma unroll
;       for (int j = 0; j < 4; ++j) {
;         wf[j] = *(const bf16x8*)(sb + j * 2048 + foff[ks]);
;         af[j] = *(const bf16x8*)(sa + j * 2048 + foff[ks]);
;       }
; #pragma unroll
;       for (int ni = 0; ni < 4; ++ni)
; #pragma unroll
;         for (int mi = 0; mi < 4; ++mi) acc[ni][mi] = __builtin_amdgcn_mfma_f32_16x16x32_bf16(wf[ni], af[mi], acc[ni][mi], 0, 0, 0);
;     }
;     asm volatile("s_waitcnt vmcnt(0)" ::: "memory");
;     __syncthreads();
;   }
;     ...
;   const int nh = n0 + wn * 64;
;   if (epi.packed(nh)) {
; #pragma unroll
;     for (int mi = 0; mi < 4; ++mi) {
;       const int m = m0 + wm * 64 + mi * 16 + fr;
;       float ss = 0.f;
;       u32x2 pk[4];
; #pragma unroll
;       for (int ni = 0; ni < 4; ++ni) pk[ni] = epi.pack(m, nh + ni * 16 + fq * 4, acc[ni][mi][0], acc[ni][mi][1], acc[ni][mi][2], acc[ni][mi][3], ss);
;       epi.finish16(m, nh, ss);
;       u16* rp = epi.rowp(m) + nh;
; #pragma unroll
;       for (int pp = 0; pp < 2; ++pp) {
;         u32x2 a = pk[2 * pp], b = pk[2 * pp + 1];
;         const u32x2 rx = __builtin_amdgcn_permlane16_swap(a.x, b.x, false, false);
;         const u32x2 ry = __builtin_amdgcn_permlane16_swap(a.y, b.y, false, false);
;         const int nst = (fq & 1) ? ((2 * pp + 1) * 16 + (fq - 1) * 4) : ((2 * pp) * 16 + fq * 4);
;         *(u32x4*)(rp + nst) = (u32x4){rx[0], ry[0], rx[1], ry[1]};
;       }
	v_mfma_f32_16x16x32_bf16 v[24:27], v[100:103], v[70:73], v[24:27]
	v_mfma_f32_16x16x32_bf16 v[44:47], v[66:69], v[70:73], v[44:47]
	v_lshl_add_u32 v72, v85, 6, v64
	v_lshl_or_b32 v70, v84, 6, s18
	v_ashrrev_i32_e32 v73, 31, v72
	v_mfma_f32_16x16x32_bf16 v[32:35], v[112:115], v[120:123], v[32:35]
	v_ashrrev_i32_e32 v71, 31, v70
	v_and_b32_e32 v64, 16, v82
	v_lshlrev_b32_e32 v82, 2, v83
	v_mfma_f32_16x16x32_bf16 v[24:27], v[108:111], v[120:123], v[24:27]
	v_cmp_eq_u32_e32 vcc, 0, v64
	s_nop 2
	v_cvt_pk_bf16_f32 v32, v32, v33
	v_cvt_pk_bf16_f32 v33, v34, v35
	v_mfma_f32_16x16x32_bf16 v[60:63], v[128:131], v[120:123], v[60:63]
	v_mfma_f32_16x16x32_bf16 v[44:47], v[124:127], v[120:123], v[44:47]
	v_cvt_pk_bf16_f32 v34, v24, v25
	v_lshlrev_b64 v[24:25], 11, v[72:73]
	s_nop 4
	v_cvt_pk_bf16_f32 v60, v60, v61
	v_cvt_pk_bf16_f32 v61, v62, v63
	v_lshl_add_u64 v[24:25], s[6:7], 0, v[24:25]
	v_cvt_pk_bf16_f32 v62, v44, v45
	v_lshlrev_b64 v[44:45], 1, v[70:71]
	v_cvt_pk_bf16_f32 v63, v46, v47
	v_lshl_add_u64 v[46:47], v[24:25], 0, v[44:45]
	v_add_u32_e32 v24, 12, v82
	v_cndmask_b32_e32 v24, v24, v82, vcc
	v_lshlrev_b32_e32 v64, 1, v24
	v_permlane16_swap_b32_e32 v60, v62
	v_permlane16_swap_b32_e32 v61, v63
	v_lshl_add_u64 v[24:25], v[46:47], 0, v[64:65]
	v_mfma_f32_16x16x32_bf16 v[40:43], v[66:69], v[74:77], v[40:43]
	v_cvt_pk_bf16_f32 v35, v26, v27
	global_store_dwordx4 v[24:25], v[60:63], off
	v_permlane16_swap_b32_e32 v32, v34
	v_mfma_f32_16x16x32_bf16 v[24:27], v[100:103], v[78:81], v[28:31]
	v_mov_b32_e32 v61, v65
	v_permlane16_swap_b32_e32 v33, v35
	s_nop 0
	v_add_u32_e32 v28, 44, v82
	v_or_b32_e32 v29, 32, v82
	v_cndmask_b32_e32 v28, v28, v29, vcc
	v_lshlrev_b32_e32 v60, 1, v28
	v_lshl_add_u64 v[46:47], v[46:47], 0, v[60:61]
	v_mfma_f32_16x16x32_bf16 v[28:31], v[128:131], v[116:119], v[56:59]
	global_store_dwordx4 v[46:47], v[32:35], off
	s_nop 1
	v_mfma_f32_16x16x32_bf16 v[32:35], v[124:127], v[116:119], v[40:43]
	v_mfma_f32_16x16x32_bf16 v[12:15], v[104:107], v[74:77], v[12:15]
	s_nop 2
	v_cvt_pk_bf16_f32 v28, v28, v29
	v_cvt_pk_bf16_f32 v29, v30, v31
	s_nop 1
	v_cvt_pk_bf16_f32 v30, v32, v33
	v_mfma_f32_16x16x32_bf16 v[0:3], v[100:103], v[74:77], v[0:3]
	v_or_b32_e32 v32, 16, v72
	v_ashrrev_i32_e32 v33, 31, v32
	v_lshlrev_b64 v[32:33], 11, v[32:33]
	v_mfma_f32_16x16x32_bf16 v[12:15], v[112:115], v[116:119], v[12:15]
	v_lshl_add_u64 v[40:41], s[6:7], 0, v[32:33]
	v_cvt_pk_bf16_f32 v31, v34, v35
	v_lshl_add_u64 v[40:41], v[40:41], 0, v[44:45]
	v_mfma_f32_16x16x32_bf16 v[0:3], v[108:111], v[116:119], v[0:3]
	v_permlane16_swap_b32_e32 v28, v30
	s_nop 2
	v_cvt_pk_bf16_f32 v12, v12, v13
	v_mfma_f32_16x16x32_bf16 v[8:11], v[104:107], v[78:81], v[8:11]
	v_cvt_pk_bf16_f32 v13, v14, v15
	s_nop 0
	v_cvt_pk_bf16_f32 v14, v0, v1
	v_cvt_pk_bf16_f32 v15, v2, v3
	v_permlane16_swap_b32_e32 v29, v31
	v_lshl_add_u64 v[42:43], v[40:41], 0, v[64:65]
	global_store_dwordx4 v[42:43], v[28:31], off
	v_permlane16_swap_b32_e32 v12, v14
	v_permlane16_swap_b32_e32 v13, v15
	v_lshl_add_u64 v[28:29], v[40:41], 0, v[60:61]
	v_mfma_f32_16x16x32_bf16 v[36:39], v[66:69], v[78:81], v[36:39]
	global_store_dwordx4 v[28:29], v[12:15], off
	v_mfma_f32_16x16x32_bf16 v[8:11], v[112:115], v[96:99], v[8:11]
	s_nop 0
	v_mfma_f32_16x16x32_bf16 v[12:15], v[108:111], v[96:99], v[24:27]
	v_mfma_f32_16x16x32_bf16 v[0:3], v[128:131], v[96:99], v[52:55]
	s_nop 4
	v_cvt_pk_bf16_f32 v8, v8, v9
	v_cvt_pk_bf16_f32 v9, v10, v11
	v_cvt_pk_bf16_f32 v10, v12, v13
	v_mfma_f32_16x16x32_bf16 v[36:39], v[124:127], v[96:99], v[36:39]
	v_or_b32_e32 v12, 32, v72
	v_ashrrev_i32_e32 v13, 31, v12
	v_lshlrev_b64 v[12:13], 11, v[12:13]
	v_mfma_f32_16x16x32_bf16 v[16:19], v[66:69], v[92:95], v[16:19]
	v_lshl_add_u64 v[12:13], s[6:7], 0, v[12:13]
	v_cvt_pk_bf16_f32 v0, v0, v1
	v_cvt_pk_bf16_f32 v1, v2, v3
	v_mfma_f32_16x16x32_bf16 v[4:7], v[104:107], v[92:95], v[4:7]
	v_cvt_pk_bf16_f32 v2, v36, v37
	v_cvt_pk_bf16_f32 v3, v38, v39
	v_lshl_add_u64 v[12:13], v[12:13], 0, v[44:45]
	v_mfma_f32_16x16x32_bf16 v[20:23], v[100:103], v[92:95], v[20:23]
	v_cvt_pk_bf16_f32 v11, v14, v15
	v_permlane16_swap_b32_e32 v0, v2
	v_permlane16_swap_b32_e32 v1, v3
	v_lshl_add_u64 v[14:15], v[12:13], 0, v[64:65]
	global_store_dwordx4 v[14:15], v[0:3], off
	v_permlane16_swap_b32_e32 v8, v10
	v_permlane16_swap_b32_e32 v9, v11
	v_lshl_add_u64 v[0:1], v[12:13], 0, v[60:61]
	v_mfma_f32_16x16x32_bf16 v[32:35], v[128:131], v[86:89], v[48:51]
	global_store_dwordx4 v[0:1], v[8:11], off
	v_mfma_f32_16x16x32_bf16 v[16:19], v[124:127], v[86:89], v[16:19]
	s_nop 0
	v_or_b32_e32 v8, 48, v72
	v_ashrrev_i32_e32 v9, 31, v8
	v_lshlrev_b64 v[8:9], 11, v[8:9]
	v_mfma_f32_16x16x32_bf16 v[4:7], v[112:115], v[86:89], v[4:7]
	v_lshl_add_u64 v[8:9], s[6:7], 0, v[8:9]
	v_cvt_pk_bf16_f32 v0, v32, v33
	v_cvt_pk_bf16_f32 v1, v34, v35
	v_mfma_f32_16x16x32_bf16 v[20:23], v[108:111], v[86:89], v[20:23]
	v_cvt_pk_bf16_f32 v2, v16, v17
	v_cvt_pk_bf16_f32 v3, v18, v19
	v_lshl_add_u64 v[8:9], v[8:9], 0, v[44:45]
	s_nop 0
	v_cvt_pk_bf16_f32 v4, v4, v5
	v_cvt_pk_bf16_f32 v5, v6, v7
	s_nop 1
	v_cvt_pk_bf16_f32 v6, v20, v21
	v_cvt_pk_bf16_f32 v7, v22, v23
	v_permlane16_swap_b32_e32 v0, v2
	v_permlane16_swap_b32_e32 v1, v3
	v_lshl_add_u64 v[10:11], v[8:9], 0, v[64:65]
	global_store_dwordx4 v[10:11], v[0:3], off
	v_permlane16_swap_b32_e32 v4, v6
	v_permlane16_swap_b32_e32 v5, v7
	v_lshl_add_u64 v[0:1], v[8:9], 0, v[60:61]
	global_store_dwordx4 v[0:1], v[4:7], off
	s_load_dword s1, s[10:11], 0x0
	s_waitcnt lgkmcnt(0)
	s_add_i32 s0, s1, s0
	s_cmpk_lt_i32 s0, 0x400
	s_cbranch_scc1 .LBB0_1044

; template <class ARow, class Epi>
; DI void gemm_tile(const ARow& arow, long a_kstride, const u16* __restrict__ Bt, long ldb, int K, int m0, int n0,
;                   const Epi& epi, char* smem) {
;     ...
;   const int fr = lane & 15, fq = lane >> 4;
;   int foff[2];
; #pragma unroll
;   for (int ks = 0; ks < 2; ++ks) foff[ks] = fr * 128 + ((((4 * ks + fq) ^ ((fr >> 1) & 7))) << 4);
;   f32x4 acc[4][4];
; #pragma unroll
;   for (int a = 0; a < 4; ++a)
; #pragma unroll
;     for (int b = 0; b < 4; ++b) acc[a][b] = (f32x4){0.f, 0.f, 0.f, 0.f};
;   const int KT = K >> 6;
;   GEMM_STAGE(0, 0);
;   asm volatile("s_waitcnt vmcnt(0)" ::: "memory");
;   __syncthreads();
;   for (int kt = 0; kt < KT; ++kt) {
;     const int cur = kt & 1;
;     if (kt + 1 < KT) GEMM_STAGE(cur ^ 1, kt + 1);
;     const char* sa = smem + cur * 32768 + wm * 64 * 128;
;     const char* sb = smem + cur * 32768 + 16384 + wn * 64 * 128;
; #pragma unroll
;     for (int ks = 0; ks < 2; ++ks) {
;       bf16x8 wf[4], af[4];
; #pragma unroll
;       for (int j = 0; j < 4; ++j) {
;         wf[j] = *(const bf16x8*)(sb + j * 2048 + foff[ks]);
;         af[j] = *(const bf16x8*)(sa + j * 2048 + foff[ks]);
;       }
; #pragma unroll
;       for (int ni = 0; ni < 4; ++ni)
; #pragma unroll
;         for (int mi = 0; mi < 4; ++mi) acc[ni][mi] = __builtin_amdgcn_mfma_f32_16x16x32_bf16(wf[ni], af[mi], acc[ni][mi], 0, 0, 0);
;     }
;     asm volatile("s_waitcnt vmcnt(0)" ::: "memory");
;     __syncthreads();
;   }
.LBB0_1173:
	s_and_b32 s6, s1, 0x8000
	v_add_u32_e32 v116, s6, v89
	v_or_b32_e32 v117, s6, v90
	v_add_u32_e32 v118, v117, v88
	v_add_u32_e32 v112, v116, v88
	ds_read_b128 v[92:95], v118 offset:16384
	ds_read_b128 v[96:99], v112
	ds_read_b128 v[100:103], v118 offset:18432
	ds_read_b128 v[104:107], v112 offset:2048
	ds_read_b128 v[108:111], v112 offset:4096
	ds_read_b128 v[112:115], v112 offset:6144
	s_xor_b32 s7, s6, 0x8000
	v_add_u32_e32 v176, s7, v91
	s_nop 0
	v_readfirstlane_b32 s6, v176
	v_add_u32_e32 v177, 0x4000, v176
	v_lshl_add_u64 v[160:161], v[66:67], 0, s[4:5]
	v_add_u32_e32 v178, 0x400, v176
	v_readfirstlane_b32 s7, v177
	s_mov_b32 m0, s6
	v_lshl_add_u64 v[162:163], v[68:69], 0, s[4:5]
	v_add_u32_e32 v179, 0x4400, v176
	v_readfirstlane_b32 s8, v178
	global_load_lds_dwordx4 v[160:161], off
	s_mov_b32 m0, s7
	v_lshl_add_u64 v[164:165], v[70:71], 0, s[4:5]
	v_add_u32_e32 v181, 0x800, v176
	v_readfirstlane_b32 s9, v179
	global_load_lds_dwordx4 v[162:163], off
	s_mov_b32 m0, s8
	v_lshl_add_u64 v[166:167], v[72:73], 0, s[4:5]
	v_add_u32_e32 v182, 0x4800, v176
	v_readfirstlane_b32 s10, v181
	global_load_lds_dwordx4 v[164:165], off
	s_mov_b32 m0, s9
	v_lshl_add_u64 v[168:169], v[74:75], 0, s[4:5]
	v_add_u32_e32 v183, 0xc00, v176
	v_readfirstlane_b32 s11, v182
	global_load_lds_dwordx4 v[166:167], off
	s_mov_b32 m0, s10
	v_lshl_add_u64 v[170:171], v[76:77], 0, s[4:5]
	v_add_u32_e32 v176, 0x4c00, v176
	v_readfirstlane_b32 s12, v183
	global_load_lds_dwordx4 v[168:169], off
	s_mov_b32 m0, s11
	v_lshl_add_u64 v[172:173], v[78:79], 0, s[4:5]
	v_readfirstlane_b32 s13, v176
	global_load_lds_dwordx4 v[170:171], off
	s_mov_b32 m0, s12
	v_lshl_add_u64 v[174:175], v[80:81], 0, s[4:5]
	global_load_lds_dwordx4 v[172:173], off
	s_mov_b32 m0, s13
	global_load_lds_dwordx4 v[174:175], off
	s_waitcnt lgkmcnt(0)
	v_mfma_f32_16x16x32_bf16 v[60:63], v[92:95], v[96:99], v[60:63]
	v_add_u32_e32 v117, v117, v87
	v_add_u32_e32 v116, v116, v87
	s_add_i32 s1, s1, 0x8000
	v_mfma_f32_16x16x32_bf16 v[56:59], v[92:95], v[104:107], v[56:59]
	s_add_u32 s4, s4, 0x80
	s_addc_u32 s5, s5, 0
	s_cmpk_eq_i32 s4, 0x780
	v_mfma_f32_16x16x32_bf16 v[48:51], v[92:95], v[108:111], v[48:51]
	v_mfma_f32_16x16x32_bf16 v[40:43], v[92:95], v[112:115], v[40:43]
	v_mfma_f32_16x16x32_bf16 v[36:39], v[100:103], v[96:99], v[36:39]
	v_mfma_f32_16x16x32_bf16 v[32:35], v[100:103], v[104:107], v[32:35]
	v_mfma_f32_16x16x32_bf16 v[28:31], v[100:103], v[108:111], v[28:31]
	v_mfma_f32_16x16x32_bf16 v[24:27], v[100:103], v[112:115], v[24:27]
	ds_read_b128 v[92:95], v118 offset:20480
	ds_read_b128 v[100:103], v118 offset:22528
	s_waitcnt lgkmcnt(1)
	v_mfma_f32_16x16x32_bf16 v[20:23], v[92:95], v[96:99], v[20:23]
	v_mfma_f32_16x16x32_bf16 v[16:19], v[92:95], v[104:107], v[16:19]
	v_mfma_f32_16x16x32_bf16 v[12:15], v[92:95], v[108:111], v[12:15]
	v_mfma_f32_16x16x32_bf16 v[8:11], v[92:95], v[112:115], v[8:11]
	ds_read_b128 v[92:95], v117 offset:16384
	s_waitcnt lgkmcnt(1)
	v_mfma_f32_16x16x32_bf16 v[4:7], v[100:103], v[96:99], v[4:7]
	v_mfma_f32_16x16x32_bf16 v[0:3], v[100:103], v[104:107], v[0:3]
	v_mfma_f32_16x16x32_bf16 v[52:55], v[100:103], v[108:111], v[52:55]
	v_mfma_f32_16x16x32_bf16 v[44:47], v[100:103], v[112:115], v[44:47]
	ds_read_b128 v[96:99], v116
	ds_read_b128 v[100:103], v117 offset:18432
	ds_read_b128 v[104:107], v116 offset:2048
	ds_read_b128 v[108:111], v116 offset:4096
	ds_read_b128 v[112:115], v116 offset:6144
	s_waitcnt lgkmcnt(4)
	v_mfma_f32_16x16x32_bf16 v[60:63], v[92:95], v[96:99], v[60:63]
	s_waitcnt lgkmcnt(2)
	v_mfma_f32_16x16x32_bf16 v[56:59], v[92:95], v[104:107], v[56:59]
	s_waitcnt lgkmcnt(1)
	v_mfma_f32_16x16x32_bf16 v[48:51], v[92:95], v[108:111], v[48:51]
	s_waitcnt lgkmcnt(0)
	v_mfma_f32_16x16x32_bf16 v[40:43], v[92:95], v[112:115], v[40:43]
	v_mfma_f32_16x16x32_bf16 v[36:39], v[100:103], v[96:99], v[36:39]
	v_mfma_f32_16x16x32_bf16 v[32:35], v[100:103], v[104:107], v[32:35]
	v_mfma_f32_16x16x32_bf16 v[28:31], v[100:103], v[108:111], v[28:31]
	v_mfma_f32_16x16x32_bf16 v[24:27], v[100:103], v[112:115], v[24:27]
	ds_read_b128 v[92:95], v117 offset:20480
	ds_read_b128 v[100:103], v117 offset:22528
	s_waitcnt lgkmcnt(0)
	s_waitcnt vmcnt(0)
	s_waitcnt vmcnt(0) lgkmcnt(0)
	v_mfma_f32_16x16x32_bf16 v[20:23], v[92:95], v[96:99], v[20:23]
	s_barrier
	v_mfma_f32_16x16x32_bf16 v[16:19], v[92:95], v[104:107], v[16:19]
	v_mfma_f32_16x16x32_bf16 v[12:15], v[92:95], v[108:111], v[12:15]
	v_mfma_f32_16x16x32_bf16 v[8:11], v[92:95], v[112:115], v[8:11]
	v_mfma_f32_16x16x32_bf16 v[4:7], v[100:103], v[96:99], v[4:7]
	v_mfma_f32_16x16x32_bf16 v[0:3], v[100:103], v[104:107], v[0:3]
	v_mfma_f32_16x16x32_bf16 v[52:55], v[100:103], v[108:111], v[52:55]
	v_mfma_f32_16x16x32_bf16 v[44:47], v[100:103], v[112:115], v[44:47]
	s_cbranch_scc0 .LBB0_1173
;   DI u32x2 pack(int, int, float a, float b, float c, float d, float&) const { u32x2 v; v.x = pack2(a, b); v.y = pack2(c, d); return v; }
; template <class ARow, class Epi>
; DI void gemm_tile(const ARow& arow, long a_kstride, const u16* __restrict__ Bt, long ldb, int K, int m0, int n0,
;                   const Epi& epi, char* smem) {
;     ...
;     for (int ks = 0; ks < 2; ++ks) {
;       bf16x8 wf[4], af[4];
; #pragma unroll
;       for (int j = 0; j < 4; ++j) {
;         wf[j] = *(const bf16x8*)(sb + j * 2048 + foff[ks]);
;         af[j] = *(const bf16x8*)(sa + j * 2048 + foff[ks]);
;       }
; #pragma unroll
;       for (int ni = 0; ni < 4; ++ni)
; #pragma unroll
;         for (int mi = 0; mi < 4; ++mi) acc[ni][mi] = __builtin_amdgcn_mfma_f32_16x16x32_bf16(wf[ni], af[mi], acc[ni][mi], 0, 0, 0);
;     }
;     asm volatile("s_waitcnt vmcnt(0)" ::: "memory");
;     __syncthreads();
;   }
;     ...
;   const int nh = n0 + wn * 64;
;   if (epi.packed(nh)) {
; #pragma unroll
;     for (int mi = 0; mi < 4; ++mi) {
;       const int m = m0 + wm * 64 + mi * 16 + fr;
;       float ss = 0.f;
;       u32x2 pk[4];
; #pragma unroll
;       for (int ni = 0; ni < 4; ++ni) pk[ni] = epi.pack(m, nh + ni * 16 + fq * 4, acc[ni][mi][0], acc[ni][mi][1], acc[ni][mi][2], acc[ni][mi][3], ss);
;       epi.finish16(m, nh, ss);
;       u16* rp = epi.rowp(m) + nh;
; #pragma unroll
;       for (int pp = 0; pp < 2; ++pp) {
;         u32x2 a = pk[2 * pp], b = pk[2 * pp + 1];
;         const u32x2 rx = __builtin_amdgcn_permlane16_swap(a.x, b.x, false, false);
;         const u32x2 ry = __builtin_amdgcn_permlane16_swap(a.y, b.y, false, false);
;         const int nst = (fq & 1) ? ((2 * pp + 1) * 16 + (fq - 1) * 4) : ((2 * pp) * 16 + fq * 4);
;         *(u32x4*)(rp + nst) = (u32x4){rx[0], ry[0], rx[1], ry[1]};
;       }
	v_add_u32_e32 v91, v90, v88
	ds_read_b128 v[66:69], v91 offset:49152
	v_add_u32_e32 v88, v89, v88
	ds_read_b128 v[70:73], v88 offset:32768
	ds_read_b128 v[74:77], v88 offset:34816
	ds_read_b128 v[78:81], v88 offset:36864
	ds_read_b128 v[92:95], v88 offset:38912
	v_add_u32_e32 v116, v90, v87
	s_waitcnt lgkmcnt(3)
	v_mfma_f32_16x16x32_bf16 v[60:63], v[66:69], v[70:73], v[60:63]
	s_waitcnt lgkmcnt(2)
	v_mfma_f32_16x16x32_bf16 v[56:59], v[66:69], v[74:77], v[56:59]
	s_waitcnt lgkmcnt(1)
	v_mfma_f32_16x16x32_bf16 v[48:51], v[66:69], v[78:81], v[48:51]
	s_waitcnt lgkmcnt(0)
	v_mfma_f32_16x16x32_bf16 v[40:43], v[66:69], v[92:95], v[40:43]
	ds_read_b128 v[66:69], v91 offset:51200
	s_waitcnt lgkmcnt(0)
	v_mfma_f32_16x16x32_bf16 v[36:39], v[66:69], v[70:73], v[36:39]
	v_mfma_f32_16x16x32_bf16 v[32:35], v[66:69], v[74:77], v[32:35]
	v_mfma_f32_16x16x32_bf16 v[96:99], v[66:69], v[78:81], v[28:31]
	v_mfma_f32_16x16x32_bf16 v[66:69], v[66:69], v[92:95], v[24:27]
	s_nop 2
	ds_read_b128 v[24:27], v91 offset:53248
	s_waitcnt lgkmcnt(0)
	v_mfma_f32_16x16x32_bf16 v[104:107], v[24:27], v[92:95], v[8:11]
	s_nop 2
	ds_read_b128 v[8:11], v91 offset:55296
	v_mfma_f32_16x16x32_bf16 v[20:23], v[24:27], v[70:73], v[20:23]
	s_waitcnt lgkmcnt(0)
	v_mfma_f32_16x16x32_bf16 v[70:73], v[8:11], v[70:73], v[4:7]
	s_nop 2
	ds_read_b128 v[4:7], v116 offset:49152
	v_mfma_f32_16x16x32_bf16 v[100:103], v[24:27], v[78:81], v[12:15]
	s_nop 2
	v_add_u32_e32 v12, v89, v87
	v_mfma_f32_16x16x32_bf16 v[16:19], v[24:27], v[74:77], v[16:19]
	ds_read_b128 v[88:91], v12 offset:32768
	ds_read_b128 v[108:111], v12 offset:36864
	ds_read_b128 v[112:115], v12 offset:38912
	v_mfma_f32_16x16x32_bf16 v[0:3], v[8:11], v[74:77], v[0:3]
	v_mfma_f32_16x16x32_bf16 v[74:77], v[8:11], v[78:81], v[52:55]
	v_mfma_f32_16x16x32_bf16 v[78:81], v[8:11], v[92:95], v[44:47]
	ds_read_b128 v[92:95], v12 offset:34816
	s_waitcnt lgkmcnt(3)
	v_mfma_f32_16x16x32_bf16 v[60:63], v[4:7], v[88:91], v[60:63]
	s_waitcnt lgkmcnt(0)
	v_mfma_f32_16x16x32_bf16 v[44:47], v[4:7], v[92:95], v[56:59]
	v_mfma_f32_16x16x32_bf16 v[28:31], v[4:7], v[108:111], v[48:51]
	v_mfma_f32_16x16x32_bf16 v[12:15], v[4:7], v[112:115], v[40:43]
	ds_read_b128 v[4:7], v116 offset:51200
	s_waitcnt lgkmcnt(0)
	v_mfma_f32_16x16x32_bf16 v[56:59], v[4:7], v[88:91], v[36:39]
	v_mfma_f32_16x16x32_bf16 v[40:43], v[4:7], v[92:95], v[32:35]
	v_mfma_f32_16x16x32_bf16 v[24:27], v[4:7], v[108:111], v[96:99]
	v_mfma_f32_16x16x32_bf16 v[8:11], v[4:7], v[112:115], v[66:69]
	ds_read_b128 v[4:7], v116 offset:53248
	s_nop 0
	ds_read_b128 v[96:99], v116 offset:55296
	s_waitcnt lgkmcnt(0)
	s_waitcnt vmcnt(0)
	s_waitcnt lgkmcnt(0)
	v_mfma_f32_16x16x32_bf16 v[32:35], v[96:99], v[92:95], v[0:3]
	s_nop 2
	v_or_b32_e32 v0, s0, v64
	v_lshl_add_u32 v66, v86, 6, v0
	v_lshl_or_b32 v68, v85, 6, s38
	v_mfma_f32_16x16x32_bf16 v[52:55], v[4:7], v[88:91], v[20:23]
	v_cmp_lt_i32_e32 vcc, s33, v68
	s_barrier
	v_mfma_f32_16x16x32_bf16 v[36:39], v[4:7], v[92:95], v[16:19]
	v_mfma_f32_16x16x32_bf16 v[20:23], v[4:7], v[108:111], v[100:103]
	v_mfma_f32_16x16x32_bf16 v[4:7], v[4:7], v[112:115], v[104:107]
	v_mfma_f32_16x16x32_bf16 v[48:51], v[96:99], v[88:91], v[70:73]
	v_mfma_f32_16x16x32_bf16 v[16:19], v[96:99], v[108:111], v[74:77]
	s_nop 1
	v_lshlrev_b32_e32 v72, 2, v84
	v_or_b32_e32 v64, v68, v72
	v_mfma_f32_16x16x32_bf16 v[0:3], v[96:99], v[112:115], v[78:81]
	s_nop 7
	v_readfirstlane_b32 s99, v68
	s_cmpk_ge_u32 s99, 0x800
	s_cbranch_scc0 .Lfe_B_not_plain
	s_cmpk_lt_u32 s99, 0xc00
	s_cbranch_scc0 .Lfe_B_not_plain
	s_load_dwordx2 s[100:101], s[56:57], 0x130
	v_and_b32_e32 v152, 1, v84
	v_mul_u32_u24_e32 v152, 12, v152
	v_lshl_add_u32 v152, v84, 2, v152
	v_add_u32_e32 v152, v152, v68
	v_lshl_add_u32 v152, v66, 12, v152
	v_lshlrev_b32_e32 v152, 1, v152
	v_add_u32_e32 v153, 0x20000, v152
	v_add_u32_e32 v154, 0x40000, v152
	v_add_u32_e32 v155, 0x60000, v152
	s_nop 3
	v_cvt_pk_bf16_f32 v120, v60, v61
	v_cvt_pk_bf16_f32 v121, v62, v63
	v_cvt_pk_bf16_f32 v122, v56, v57
	v_cvt_pk_bf16_f32 v123, v58, v59
	v_cvt_pk_bf16_f32 v124, v52, v53
	v_cvt_pk_bf16_f32 v125, v54, v55
	v_cvt_pk_bf16_f32 v126, v48, v49
	v_cvt_pk_bf16_f32 v127, v50, v51
	s_nop 1
	v_permlane16_swap_b32_e32 v120, v122
	v_permlane16_swap_b32_e32 v121, v123
	v_permlane16_swap_b32_e32 v124, v126
	v_permlane16_swap_b32_e32 v125, v127
	s_waitcnt lgkmcnt(0)
	global_store_dwordx4 v152, v[120:123], s[100:101]
	global_store_dwordx4 v152, v[124:127], s[100:101] offset:64
	v_cvt_pk_bf16_f32 v128, v44, v45
	v_cvt_pk_bf16_f32 v129, v46, v47
	v_cvt_pk_bf16_f32 v130, v40, v41
	v_cvt_pk_bf16_f32 v131, v42, v43
	v_cvt_pk_bf16_f32 v132, v36, v37
	v_cvt_pk_bf16_f32 v133, v38, v39
	v_cvt_pk_bf16_f32 v134, v32, v33
	v_cvt_pk_bf16_f32 v135, v34, v35
	s_nop 1
	v_permlane16_swap_b32_e32 v128, v130
	v_permlane16_swap_b32_e32 v129, v131
	v_permlane16_swap_b32_e32 v132, v134
	v_permlane16_swap_b32_e32 v133, v135
	global_store_dwordx4 v153, v[128:131], s[100:101]
	global_store_dwordx4 v153, v[132:135], s[100:101] offset:64
	v_cvt_pk_bf16_f32 v136, v28, v29
	v_cvt_pk_bf16_f32 v137, v30, v31
	v_cvt_pk_bf16_f32 v138, v24, v25
	v_cvt_pk_bf16_f32 v139, v26, v27
	v_cvt_pk_bf16_f32 v140, v20, v21
	v_cvt_pk_bf16_f32 v141, v22, v23
	v_cvt_pk_bf16_f32 v142, v16, v17
	v_cvt_pk_bf16_f32 v143, v18, v19
	s_nop 1
	v_permlane16_swap_b32_e32 v136, v138
	v_permlane16_swap_b32_e32 v137, v139
	v_permlane16_swap_b32_e32 v140, v142
	v_permlane16_swap_b32_e32 v141, v143
	global_store_dwordx4 v154, v[136:139], s[100:101]
	global_store_dwordx4 v154, v[140:143], s[100:101] offset:64
	v_cvt_pk_bf16_f32 v144, v12, v13
	v_cvt_pk_bf16_f32 v145, v14, v15
	v_cvt_pk_bf16_f32 v146, v8, v9
	v_cvt_pk_bf16_f32 v147, v10, v11
	v_cvt_pk_bf16_f32 v148, v4, v5
	v_cvt_pk_bf16_f32 v149, v6, v7
	v_cvt_pk_bf16_f32 v150, v0, v1
	v_cvt_pk_bf16_f32 v151, v2, v3
	s_nop 1
	v_permlane16_swap_b32_e32 v144, v146
	v_permlane16_swap_b32_e32 v145, v147
	v_permlane16_swap_b32_e32 v148, v150
	v_permlane16_swap_b32_e32 v149, v151
	global_store_dwordx4 v155, v[144:147], s[100:101]
	global_store_dwordx4 v155, v[148:151], s[100:101] offset:64
	s_branch .Lfe_join_B

; template <class ARow, class Epi>
; DI void gemm_tile(const ARow& arow, long a_kstride, const u16* __restrict__ Bt, long ldb, int K, int m0, int n0,
;                   const Epi& epi, char* smem) {
;     ...
;   const int fr = lane & 15, fq = lane >> 4;
;   int foff[2];
; #pragma unroll
;   for (int ks = 0; ks < 2; ++ks) foff[ks] = fr * 128 + ((((4 * ks + fq) ^ ((fr >> 1) & 7))) << 4);
;   f32x4 acc[4][4];
; #pragma unroll
;   for (int a = 0; a < 4; ++a)
; #pragma unroll
;     for (int b = 0; b < 4; ++b) acc[a][b] = (f32x4){0.f, 0.f, 0.f, 0.f};
;   const int KT = K >> 6;
;   GEMM_STAGE(0, 0);
;   asm volatile("s_waitcnt vmcnt(0)" ::: "memory");
;   __syncthreads();
;   for (int kt = 0; kt < KT; ++kt) {
;     const int cur = kt & 1;
;     if (kt + 1 < KT) GEMM_STAGE(cur ^ 1, kt + 1);
;     const char* sa = smem + cur * 32768 + wm * 64 * 128;
;     const char* sb = smem + cur * 32768 + 16384 + wn * 64 * 128;
; #pragma unroll
;     for (int ks = 0; ks < 2; ++ks) {
;       bf16x8 wf[4], af[4];
; #pragma unroll
;       for (int j = 0; j < 4; ++j) {
;         wf[j] = *(const bf16x8*)(sb + j * 2048 + foff[ks]);
;         af[j] = *(const bf16x8*)(sa + j * 2048 + foff[ks]);
;       }
; #pragma unroll
;       for (int ni = 0; ni < 4; ++ni)
; #pragma unroll
;         for (int mi = 0; mi < 4; ++mi) acc[ni][mi] = __builtin_amdgcn_mfma_f32_16x16x32_bf16(wf[ni], af[mi], acc[ni][mi], 0, 0, 0);
;     }
;     asm volatile("s_waitcnt vmcnt(0)" ::: "memory");
;     __syncthreads();
;   }
.LBB0_1702:
	s_and_b32 s6, s1, 0x8000
	v_add_u32_e32 v91, s6, v88
	v_or_b32_e32 v116, s6, v89
	v_add_u32_e32 v117, v116, v87
	v_add_u32_e32 v112, v91, v87
	ds_read_b128 v[92:95], v117 offset:16384
	ds_read_b128 v[96:99], v112
	ds_read_b128 v[100:103], v117 offset:18432
	ds_read_b128 v[104:107], v112 offset:2048
	ds_read_b128 v[108:111], v112 offset:4096
	ds_read_b128 v[112:115], v112 offset:6144
	s_xor_b32 s7, s6, 0x8000
	v_add_u32_e32 v176, s7, v90
	s_nop 0
	v_readfirstlane_b32 s6, v176
	v_add_u32_e32 v177, 0x4000, v176
	v_lshl_add_u64 v[160:161], v[66:67], 0, s[4:5]
	v_add_u32_e32 v178, 0x400, v176
	v_readfirstlane_b32 s7, v177
	s_mov_b32 m0, s6
	v_lshl_add_u64 v[162:163], v[68:69], 0, s[4:5]
	v_add_u32_e32 v179, 0x4400, v176
	v_readfirstlane_b32 s8, v178
	global_load_lds_dwordx4 v[160:161], off
	s_mov_b32 m0, s7
	v_lshl_add_u64 v[164:165], v[70:71], 0, s[4:5]
	v_add_u32_e32 v181, 0x800, v176
	v_readfirstlane_b32 s9, v179
	global_load_lds_dwordx4 v[162:163], off
	s_mov_b32 m0, s8
	v_lshl_add_u64 v[166:167], v[72:73], 0, s[4:5]
	v_add_u32_e32 v182, 0x4800, v176
	v_readfirstlane_b32 s10, v181
	global_load_lds_dwordx4 v[164:165], off
	s_mov_b32 m0, s9
	v_lshl_add_u64 v[168:169], v[74:75], 0, s[4:5]
	v_add_u32_e32 v183, 0xc00, v176
	v_readfirstlane_b32 s11, v182
	global_load_lds_dwordx4 v[166:167], off
	s_mov_b32 m0, s10
	v_lshl_add_u64 v[170:171], v[76:77], 0, s[4:5]
	v_add_u32_e32 v176, 0x4c00, v176
	v_readfirstlane_b32 s26, v183
	global_load_lds_dwordx4 v[168:169], off
	s_mov_b32 m0, s11
	v_lshl_add_u64 v[172:173], v[78:79], 0, s[4:5]
	v_readfirstlane_b32 s27, v176
	global_load_lds_dwordx4 v[170:171], off
	s_mov_b32 m0, s26
	v_lshl_add_u64 v[174:175], v[80:81], 0, s[4:5]
	global_load_lds_dwordx4 v[172:173], off
	s_mov_b32 m0, s27
	global_load_lds_dwordx4 v[174:175], off
	s_waitcnt lgkmcnt(0)
	v_mfma_f32_16x16x32_bf16 v[60:63], v[92:95], v[96:99], v[60:63]
	v_add_u32_e32 v116, v116, v86
	v_add_u32_e32 v91, v91, v86
	s_add_i32 s1, s1, 0x8000
	v_mfma_f32_16x16x32_bf16 v[56:59], v[92:95], v[104:107], v[56:59]
	s_add_u32 s4, s4, 0x80
	s_addc_u32 s5, s5, 0
	s_cmpk_eq_i32 s4, 0x780
	v_mfma_f32_16x16x32_bf16 v[48:51], v[92:95], v[108:111], v[48:51]
	v_mfma_f32_16x16x32_bf16 v[40:43], v[92:95], v[112:115], v[40:43]
	v_mfma_f32_16x16x32_bf16 v[36:39], v[100:103], v[96:99], v[36:39]
	v_mfma_f32_16x16x32_bf16 v[32:35], v[100:103], v[104:107], v[32:35]
	v_mfma_f32_16x16x32_bf16 v[28:31], v[100:103], v[108:111], v[28:31]
	v_mfma_f32_16x16x32_bf16 v[24:27], v[100:103], v[112:115], v[24:27]
	ds_read_b128 v[92:95], v117 offset:20480
	ds_read_b128 v[100:103], v117 offset:22528
	s_waitcnt lgkmcnt(1)
	v_mfma_f32_16x16x32_bf16 v[20:23], v[92:95], v[96:99], v[20:23]
	v_mfma_f32_16x16x32_bf16 v[16:19], v[92:95], v[104:107], v[16:19]
	v_mfma_f32_16x16x32_bf16 v[12:15], v[92:95], v[108:111], v[12:15]
	v_mfma_f32_16x16x32_bf16 v[8:11], v[92:95], v[112:115], v[8:11]
	ds_read_b128 v[92:95], v116 offset:16384
	s_waitcnt lgkmcnt(1)
	v_mfma_f32_16x16x32_bf16 v[4:7], v[100:103], v[96:99], v[4:7]
	v_mfma_f32_16x16x32_bf16 v[0:3], v[100:103], v[104:107], v[0:3]
	v_mfma_f32_16x16x32_bf16 v[52:55], v[100:103], v[108:111], v[52:55]
	v_mfma_f32_16x16x32_bf16 v[44:47], v[100:103], v[112:115], v[44:47]
	ds_read_b128 v[96:99], v91
	ds_read_b128 v[100:103], v116 offset:18432
	ds_read_b128 v[104:107], v91 offset:2048
	ds_read_b128 v[108:111], v91 offset:4096
	ds_read_b128 v[112:115], v91 offset:6144
	s_waitcnt lgkmcnt(4)
	v_mfma_f32_16x16x32_bf16 v[60:63], v[92:95], v[96:99], v[60:63]
	s_waitcnt lgkmcnt(2)
	v_mfma_f32_16x16x32_bf16 v[56:59], v[92:95], v[104:107], v[56:59]
	s_waitcnt lgkmcnt(1)
	v_mfma_f32_16x16x32_bf16 v[48:51], v[92:95], v[108:111], v[48:51]
	s_waitcnt lgkmcnt(0)
	v_mfma_f32_16x16x32_bf16 v[40:43], v[92:95], v[112:115], v[40:43]
	v_mfma_f32_16x16x32_bf16 v[36:39], v[100:103], v[96:99], v[36:39]
	v_mfma_f32_16x16x32_bf16 v[32:35], v[100:103], v[104:107], v[32:35]
	v_mfma_f32_16x16x32_bf16 v[28:31], v[100:103], v[108:111], v[28:31]
	v_mfma_f32_16x16x32_bf16 v[24:27], v[100:103], v[112:115], v[24:27]
	ds_read_b128 v[92:95], v116 offset:20480
	ds_read_b128 v[100:103], v116 offset:22528
	s_waitcnt lgkmcnt(0)
	s_waitcnt vmcnt(0)
	s_waitcnt vmcnt(0) lgkmcnt(0)
	v_mfma_f32_16x16x32_bf16 v[20:23], v[92:95], v[96:99], v[20:23]
	s_barrier
	v_mfma_f32_16x16x32_bf16 v[16:19], v[92:95], v[104:107], v[16:19]
	v_mfma_f32_16x16x32_bf16 v[12:15], v[92:95], v[108:111], v[12:15]
	v_mfma_f32_16x16x32_bf16 v[8:11], v[92:95], v[112:115], v[8:11]
	v_mfma_f32_16x16x32_bf16 v[4:7], v[100:103], v[96:99], v[4:7]
	v_mfma_f32_16x16x32_bf16 v[0:3], v[100:103], v[104:107], v[0:3]
	v_mfma_f32_16x16x32_bf16 v[52:55], v[100:103], v[108:111], v[52:55]
	v_mfma_f32_16x16x32_bf16 v[44:47], v[100:103], v[112:115], v[44:47]
	s_cbranch_scc0 .LBB0_1702
;   DI u32x2 pack(int, int, float a, float b, float c, float d, float&) const { u32x2 v; v.x = pack2(a, b); v.y = pack2(c, d); return v; }
; template <class ARow, class Epi>
; DI void gemm_tile(const ARow& arow, long a_kstride, const u16* __restrict__ Bt, long ldb, int K, int m0, int n0,
;                   const Epi& epi, char* smem) {
;     ...
;     for (int ks = 0; ks < 2; ++ks) {
;       bf16x8 wf[4], af[4];
; #pragma unroll
;       for (int j = 0; j < 4; ++j) {
;         wf[j] = *(const bf16x8*)(sb + j * 2048 + foff[ks]);
;         af[j] = *(const bf16x8*)(sa + j * 2048 + foff[ks]);
;       }
; #pragma unroll
;       for (int ni = 0; ni < 4; ++ni)
; #pragma unroll
;         for (int mi = 0; mi < 4; ++mi) acc[ni][mi] = __builtin_amdgcn_mfma_f32_16x16x32_bf16(wf[ni], af[mi], acc[ni][mi], 0, 0, 0);
;     }
;     asm volatile("s_waitcnt vmcnt(0)" ::: "memory");
;     __syncthreads();
;   }
;     ...
;   const int nh = n0 + wn * 64;
;   if (epi.packed(nh)) {
; #pragma unroll
;     for (int mi = 0; mi < 4; ++mi) {
;       const int m = m0 + wm * 64 + mi * 16 + fr;
;       float ss = 0.f;
;       u32x2 pk[4];
; #pragma unroll
;       for (int ni = 0; ni < 4; ++ni) pk[ni] = epi.pack(m, nh + ni * 16 + fq * 4, acc[ni][mi][0], acc[ni][mi][1], acc[ni][mi][2], acc[ni][mi][3], ss);
;       epi.finish16(m, nh, ss);
;       u16* rp = epi.rowp(m) + nh;
; #pragma unroll
;       for (int pp = 0; pp < 2; ++pp) {
;         u32x2 a = pk[2 * pp], b = pk[2 * pp + 1];
;         const u32x2 rx = __builtin_amdgcn_permlane16_swap(a.x, b.x, false, false);
;         const u32x2 ry = __builtin_amdgcn_permlane16_swap(a.y, b.y, false, false);
;         const int nst = (fq & 1) ? ((2 * pp + 1) * 16 + (fq - 1) * 4) : ((2 * pp) * 16 + fq * 4);
;         *(u32x4*)(rp + nst) = (u32x4){rx[0], ry[0], rx[1], ry[1]};
;       }
	v_add_u32_e32 v106, v89, v87
	ds_read_b128 v[66:69], v106 offset:49152
	v_add_u32_e32 v87, v88, v87
	ds_read_b128 v[70:73], v87 offset:32768
	ds_read_b128 v[74:77], v87 offset:34816
	ds_read_b128 v[78:81], v87 offset:36864
	ds_read_b128 v[90:93], v87 offset:38912
	v_add_u32_e32 v114, v89, v86
	s_waitcnt lgkmcnt(3)
	v_mfma_f32_16x16x32_bf16 v[60:63], v[66:69], v[70:73], v[60:63]
	s_waitcnt lgkmcnt(2)
	v_mfma_f32_16x16x32_bf16 v[56:59], v[66:69], v[74:77], v[56:59]
	s_waitcnt lgkmcnt(1)
	v_mfma_f32_16x16x32_bf16 v[48:51], v[66:69], v[78:81], v[48:51]
	s_waitcnt lgkmcnt(0)
	v_mfma_f32_16x16x32_bf16 v[40:43], v[66:69], v[90:93], v[40:43]
	ds_read_b128 v[66:69], v106 offset:51200
	s_waitcnt lgkmcnt(0)
	v_mfma_f32_16x16x32_bf16 v[36:39], v[66:69], v[70:73], v[36:39]
	v_mfma_f32_16x16x32_bf16 v[32:35], v[66:69], v[74:77], v[32:35]
	v_mfma_f32_16x16x32_bf16 v[94:97], v[66:69], v[78:81], v[28:31]
	v_mfma_f32_16x16x32_bf16 v[66:69], v[66:69], v[90:93], v[24:27]
	s_nop 2
	ds_read_b128 v[24:27], v106 offset:53248
	s_waitcnt lgkmcnt(0)
	v_mfma_f32_16x16x32_bf16 v[102:105], v[24:27], v[90:93], v[8:11]
	s_nop 2
	ds_read_b128 v[8:11], v106 offset:55296
	v_mfma_f32_16x16x32_bf16 v[20:23], v[24:27], v[70:73], v[20:23]
	s_waitcnt lgkmcnt(0)
	v_mfma_f32_16x16x32_bf16 v[70:73], v[8:11], v[70:73], v[4:7]
	s_nop 2
	ds_read_b128 v[4:7], v114 offset:49152
	v_mfma_f32_16x16x32_bf16 v[98:101], v[24:27], v[78:81], v[12:15]
	s_nop 2
	v_add_u32_e32 v12, v88, v86
	v_mfma_f32_16x16x32_bf16 v[16:19], v[24:27], v[74:77], v[16:19]
	ds_read_b128 v[86:89], v12 offset:32768
	ds_read_b128 v[106:109], v12 offset:36864
	ds_read_b128 v[110:113], v12 offset:38912
	v_mfma_f32_16x16x32_bf16 v[0:3], v[8:11], v[74:77], v[0:3]
	v_mfma_f32_16x16x32_bf16 v[74:77], v[8:11], v[78:81], v[52:55]
	v_mfma_f32_16x16x32_bf16 v[78:81], v[8:11], v[90:93], v[44:47]
	ds_read_b128 v[90:93], v12 offset:34816
	s_waitcnt lgkmcnt(3)
	v_mfma_f32_16x16x32_bf16 v[60:63], v[4:7], v[86:89], v[60:63]
	s_waitcnt lgkmcnt(0)
	v_mfma_f32_16x16x32_bf16 v[44:47], v[4:7], v[90:93], v[56:59]
	v_mfma_f32_16x16x32_bf16 v[28:31], v[4:7], v[106:109], v[48:51]
	v_mfma_f32_16x16x32_bf16 v[12:15], v[4:7], v[110:113], v[40:43]
	ds_read_b128 v[4:7], v114 offset:51200
	s_waitcnt lgkmcnt(0)
	v_mfma_f32_16x16x32_bf16 v[56:59], v[4:7], v[86:89], v[36:39]
	v_mfma_f32_16x16x32_bf16 v[40:43], v[4:7], v[90:93], v[32:35]
	v_mfma_f32_16x16x32_bf16 v[24:27], v[4:7], v[106:109], v[94:97]
	v_mfma_f32_16x16x32_bf16 v[8:11], v[4:7], v[110:113], v[66:69]
	ds_read_b128 v[4:7], v114 offset:53248
	s_nop 0
	ds_read_b128 v[94:97], v114 offset:55296
	s_waitcnt lgkmcnt(0)
	s_waitcnt vmcnt(0)
	s_waitcnt lgkmcnt(0)
	v_mfma_f32_16x16x32_bf16 v[32:35], v[94:97], v[90:93], v[0:3]
	s_nop 2
	v_or_b32_e32 v0, s0, v64
	v_lshl_or_b32 v66, v84, 6, s35
	v_lshlrev_b32_e32 v68, 2, v83
	v_mfma_f32_16x16x32_bf16 v[52:55], v[4:7], v[86:89], v[20:23]
	v_cmp_lt_i32_e32 vcc, s30, v66
	v_or_b32_e32 v64, v66, v68
	v_mfma_f32_16x16x32_bf16 v[36:39], v[4:7], v[90:93], v[16:19]
	s_barrier
	v_mfma_f32_16x16x32_bf16 v[20:23], v[4:7], v[106:109], v[98:101]
	v_mfma_f32_16x16x32_bf16 v[4:7], v[4:7], v[110:113], v[102:105]
	v_mfma_f32_16x16x32_bf16 v[48:51], v[94:97], v[86:89], v[70:73]
	v_mfma_f32_16x16x32_bf16 v[16:19], v[94:97], v[106:109], v[74:77]
	s_nop 2
	v_lshl_add_u32 v74, v85, 6, v0
	v_mfma_f32_16x16x32_bf16 v[0:3], v[94:97], v[110:113], v[78:81]
	s_nop 7
	v_readfirstlane_b32 s99, v66
	s_cmpk_ge_u32 s99, 0x300
	s_cbranch_scc0 .Lfe_C_not_plain
	s_cmpk_lt_u32 s99, 0xa00
	s_cbranch_scc0 .Lfe_C_not_plain
	s_load_dwordx2 s[100:101], s[56:57], 0x130
	v_and_b32_e32 v152, 1, v83
	v_mul_u32_u24_e32 v152, 12, v152
	v_lshl_add_u32 v152, v83, 2, v152
	v_add_u32_e32 v152, v152, v66
	v_mul_u32_u24_e32 v153, 0xe00, v74
	v_add_u32_e32 v152, v152, v153
	v_lshlrev_b32_e32 v152, 1, v152
	v_add_u32_e32 v153, 0x1c000, v152
	v_add_u32_e32 v154, 0x38000, v152
	v_add_u32_e32 v155, 0x54000, v152
	s_nop 3
	v_cvt_pk_bf16_f32 v120, v60, v61
	v_cvt_pk_bf16_f32 v121, v62, v63
	v_cvt_pk_bf16_f32 v122, v56, v57
	v_cvt_pk_bf16_f32 v123, v58, v59
	v_cvt_pk_bf16_f32 v124, v52, v53
	v_cvt_pk_bf16_f32 v125, v54, v55
	v_cvt_pk_bf16_f32 v126, v48, v49
	v_cvt_pk_bf16_f32 v127, v50, v51
	s_nop 1
	v_permlane16_swap_b32_e32 v120, v122
	v_permlane16_swap_b32_e32 v121, v123
	v_permlane16_swap_b32_e32 v124, v126
	v_permlane16_swap_b32_e32 v125, v127
	s_waitcnt lgkmcnt(0)
	global_store_dwordx4 v152, v[120:123], s[100:101]
	global_store_dwordx4 v152, v[124:127], s[100:101] offset:64
	v_cvt_pk_bf16_f32 v128, v44, v45
	v_cvt_pk_bf16_f32 v129, v46, v47
	v_cvt_pk_bf16_f32 v130, v40, v41
	v_cvt_pk_bf16_f32 v131, v42, v43
	v_cvt_pk_bf16_f32 v132, v36, v37
	v_cvt_pk_bf16_f32 v133, v38, v39
	v_cvt_pk_bf16_f32 v134, v32, v33
	v_cvt_pk_bf16_f32 v135, v34, v35
	s_nop 1
	v_permlane16_swap_b32_e32 v128, v130
	v_permlane16_swap_b32_e32 v129, v131
	v_permlane16_swap_b32_e32 v132, v134
	v_permlane16_swap_b32_e32 v133, v135
	global_store_dwordx4 v153, v[128:131], s[100:101]
	global_store_dwordx4 v153, v[132:135], s[100:101] offset:64
	v_cvt_pk_bf16_f32 v136, v28, v29
	v_cvt_pk_bf16_f32 v137, v30, v31
	v_cvt_pk_bf16_f32 v138, v24, v25
	v_cvt_pk_bf16_f32 v139, v26, v27
	v_cvt_pk_bf16_f32 v140, v20, v21
	v_cvt_pk_bf16_f32 v141, v22, v23
	v_cvt_pk_bf16_f32 v142, v16, v17
	v_cvt_pk_bf16_f32 v143, v18, v19
	s_nop 1
	v_permlane16_swap_b32_e32 v136, v138
	v_permlane16_swap_b32_e32 v137, v139
	v_permlane16_swap_b32_e32 v140, v142
	v_permlane16_swap_b32_e32 v141, v143
	global_store_dwordx4 v154, v[136:139], s[100:101]
	global_store_dwordx4 v154, v[140:143], s[100:101] offset:64
	v_cvt_pk_bf16_f32 v144, v12, v13
	v_cvt_pk_bf16_f32 v145, v14, v15
	v_cvt_pk_bf16_f32 v146, v8, v9
	v_cvt_pk_bf16_f32 v147, v10, v11
	v_cvt_pk_bf16_f32 v148, v4, v5
	v_cvt_pk_bf16_f32 v149, v6, v7
	v_cvt_pk_bf16_f32 v150, v0, v1
	v_cvt_pk_bf16_f32 v151, v2, v3
	s_nop 1
	v_permlane16_swap_b32_e32 v144, v146
	v_permlane16_swap_b32_e32 v145, v147
	v_permlane16_swap_b32_e32 v148, v150
	v_permlane16_swap_b32_e32 v149, v151
	global_store_dwordx4 v155, v[144:147], s[100:101]
	global_store_dwordx4 v155, v[148:151], s[100:101] offset:64
	s_branch .Lfe_join_C

; template <class ARow, class Epi>
; DI void gemm_tile(const ARow& arow, long a_kstride, const u16* __restrict__ Bt, long ldb, int K, int m0, int n0,
;                   const Epi& epi, char* smem) {
;     ...
;   const int fr = lane & 15, fq = lane >> 4;
;   int foff[2];
; #pragma unroll
;   for (int ks = 0; ks < 2; ++ks) foff[ks] = fr * 128 + ((((4 * ks + fq) ^ ((fr >> 1) & 7))) << 4);
;   f32x4 acc[4][4];
; #pragma unroll
;   for (int a = 0; a < 4; ++a)
; #pragma unroll
;     for (int b = 0; b < 4; ++b) acc[a][b] = (f32x4){0.f, 0.f, 0.f, 0.f};
;   const int KT = K >> 6;
;   GEMM_STAGE(0, 0);
;   asm volatile("s_waitcnt vmcnt(0)" ::: "memory");
;   __syncthreads();
;   for (int kt = 0; kt < KT; ++kt) {
;     const int cur = kt & 1;
;     if (kt + 1 < KT) GEMM_STAGE(cur ^ 1, kt + 1);
;     const char* sa = smem + cur * 32768 + wm * 64 * 128;
;     const char* sb = smem + cur * 32768 + 16384 + wn * 64 * 128;
; #pragma unroll
;     for (int ks = 0; ks < 2; ++ks) {
;       bf16x8 wf[4], af[4];
; #pragma unroll
;       for (int j = 0; j < 4; ++j) {
;         wf[j] = *(const bf16x8*)(sb + j * 2048 + foff[ks]);
;         af[j] = *(const bf16x8*)(sa + j * 2048 + foff[ks]);
;       }
; #pragma unroll
;       for (int ni = 0; ni < 4; ++ni)
; #pragma unroll
;         for (int mi = 0; mi < 4; ++mi) acc[ni][mi] = __builtin_amdgcn_mfma_f32_16x16x32_bf16(wf[ni], af[mi], acc[ni][mi], 0, 0, 0);
;     }
;     asm volatile("s_waitcnt vmcnt(0)" ::: "memory");
;     __syncthreads();
;   }
.LBB0_2314:
	s_and_b32 s6, s1, 0x8000
	v_add_u32_e32 v91, s6, v88
	v_or_b32_e32 v116, s6, v89
	v_add_u32_e32 v117, v116, v87
	v_add_u32_e32 v112, v91, v87
	ds_read_b128 v[92:95], v117 offset:16384
	ds_read_b128 v[96:99], v112
	ds_read_b128 v[100:103], v117 offset:18432
	ds_read_b128 v[104:107], v112 offset:2048
	ds_read_b128 v[108:111], v112 offset:4096
	ds_read_b128 v[112:115], v112 offset:6144
	s_xor_b32 s7, s6, 0x8000
	v_add_u32_e32 v176, s7, v90
	s_nop 0
	v_readfirstlane_b32 s6, v176
	v_add_u32_e32 v177, 0x4000, v176
	v_lshl_add_u64 v[160:161], v[66:67], 0, s[4:5]
	v_add_u32_e32 v178, 0x400, v176
	v_readfirstlane_b32 s7, v177
	s_mov_b32 m0, s6
	v_lshl_add_u64 v[162:163], v[68:69], 0, s[4:5]
	v_add_u32_e32 v179, 0x4400, v176
	v_readfirstlane_b32 s8, v178
	global_load_lds_dwordx4 v[160:161], off
	s_mov_b32 m0, s7
	v_lshl_add_u64 v[164:165], v[70:71], 0, s[4:5]
	v_add_u32_e32 v181, 0x800, v176
	v_readfirstlane_b32 s9, v179
	global_load_lds_dwordx4 v[162:163], off
	s_mov_b32 m0, s8
	v_lshl_add_u64 v[166:167], v[72:73], 0, s[4:5]
	v_add_u32_e32 v182, 0x4800, v176
	v_readfirstlane_b32 s10, v181
	global_load_lds_dwordx4 v[164:165], off
	s_mov_b32 m0, s9
	v_lshl_add_u64 v[168:169], v[74:75], 0, s[4:5]
	v_add_u32_e32 v183, 0xc00, v176
	v_readfirstlane_b32 s11, v182
	global_load_lds_dwordx4 v[166:167], off
	s_mov_b32 m0, s10
	v_lshl_add_u64 v[170:171], v[76:77], 0, s[4:5]
	v_add_u32_e32 v176, 0x4c00, v176
	v_readfirstlane_b32 s26, v183
	global_load_lds_dwordx4 v[168:169], off
	s_mov_b32 m0, s11
	v_lshl_add_u64 v[172:173], v[78:79], 0, s[4:5]
	v_readfirstlane_b32 s27, v176
	global_load_lds_dwordx4 v[170:171], off
	s_mov_b32 m0, s26
	v_lshl_add_u64 v[174:175], v[80:81], 0, s[4:5]
	global_load_lds_dwordx4 v[172:173], off
	s_mov_b32 m0, s27
	global_load_lds_dwordx4 v[174:175], off
	s_waitcnt lgkmcnt(0)
	v_mfma_f32_16x16x32_bf16 v[60:63], v[92:95], v[96:99], v[60:63]
	v_add_u32_e32 v116, v116, v86
	v_add_u32_e32 v91, v91, v86
	s_add_i32 s1, s1, 0x8000
	v_mfma_f32_16x16x32_bf16 v[56:59], v[92:95], v[104:107], v[56:59]
	s_add_u32 s4, s4, 0x80
	s_addc_u32 s5, s5, 0
	s_cmpk_eq_i32 s4, 0x780
	v_mfma_f32_16x16x32_bf16 v[48:51], v[92:95], v[108:111], v[48:51]
	v_mfma_f32_16x16x32_bf16 v[40:43], v[92:95], v[112:115], v[40:43]
	v_mfma_f32_16x16x32_bf16 v[36:39], v[100:103], v[96:99], v[36:39]
	v_mfma_f32_16x16x32_bf16 v[32:35], v[100:103], v[104:107], v[32:35]
	v_mfma_f32_16x16x32_bf16 v[28:31], v[100:103], v[108:111], v[28:31]
	v_mfma_f32_16x16x32_bf16 v[24:27], v[100:103], v[112:115], v[24:27]
	ds_read_b128 v[92:95], v117 offset:20480
	ds_read_b128 v[100:103], v117 offset:22528
	s_waitcnt lgkmcnt(1)
	v_mfma_f32_16x16x32_bf16 v[20:23], v[92:95], v[96:99], v[20:23]
	v_mfma_f32_16x16x32_bf16 v[16:19], v[92:95], v[104:107], v[16:19]
	v_mfma_f32_16x16x32_bf16 v[12:15], v[92:95], v[108:111], v[12:15]
	v_mfma_f32_16x16x32_bf16 v[8:11], v[92:95], v[112:115], v[8:11]
	ds_read_b128 v[92:95], v116 offset:16384
	s_waitcnt lgkmcnt(1)
	v_mfma_f32_16x16x32_bf16 v[4:7], v[100:103], v[96:99], v[4:7]
	v_mfma_f32_16x16x32_bf16 v[0:3], v[100:103], v[104:107], v[0:3]
	v_mfma_f32_16x16x32_bf16 v[52:55], v[100:103], v[108:111], v[52:55]
	v_mfma_f32_16x16x32_bf16 v[44:47], v[100:103], v[112:115], v[44:47]
	ds_read_b128 v[96:99], v91
	ds_read_b128 v[100:103], v116 offset:18432
	ds_read_b128 v[104:107], v91 offset:2048
	ds_read_b128 v[108:111], v91 offset:4096
	ds_read_b128 v[112:115], v91 offset:6144
	s_waitcnt lgkmcnt(4)
	v_mfma_f32_16x16x32_bf16 v[60:63], v[92:95], v[96:99], v[60:63]
	s_waitcnt lgkmcnt(2)
	v_mfma_f32_16x16x32_bf16 v[56:59], v[92:95], v[104:107], v[56:59]
	s_waitcnt lgkmcnt(1)
	v_mfma_f32_16x16x32_bf16 v[48:51], v[92:95], v[108:111], v[48:51]
	s_waitcnt lgkmcnt(0)
	v_mfma_f32_16x16x32_bf16 v[40:43], v[92:95], v[112:115], v[40:43]
	v_mfma_f32_16x16x32_bf16 v[36:39], v[100:103], v[96:99], v[36:39]
	v_mfma_f32_16x16x32_bf16 v[32:35], v[100:103], v[104:107], v[32:35]
	v_mfma_f32_16x16x32_bf16 v[28:31], v[100:103], v[108:111], v[28:31]
	v_mfma_f32_16x16x32_bf16 v[24:27], v[100:103], v[112:115], v[24:27]
	ds_read_b128 v[92:95], v116 offset:20480
	ds_read_b128 v[100:103], v116 offset:22528
	s_waitcnt lgkmcnt(0)
	s_waitcnt vmcnt(0)
	s_waitcnt vmcnt(0) lgkmcnt(0)
	v_mfma_f32_16x16x32_bf16 v[20:23], v[92:95], v[96:99], v[20:23]
	s_barrier
	v_mfma_f32_16x16x32_bf16 v[16:19], v[92:95], v[104:107], v[16:19]
	v_mfma_f32_16x16x32_bf16 v[12:15], v[92:95], v[108:111], v[12:15]
	v_mfma_f32_16x16x32_bf16 v[8:11], v[92:95], v[112:115], v[8:11]
	v_mfma_f32_16x16x32_bf16 v[4:7], v[100:103], v[96:99], v[4:7]
	v_mfma_f32_16x16x32_bf16 v[0:3], v[100:103], v[104:107], v[0:3]
	v_mfma_f32_16x16x32_bf16 v[52:55], v[100:103], v[108:111], v[52:55]
	v_mfma_f32_16x16x32_bf16 v[44:47], v[100:103], v[112:115], v[44:47]
	s_cbranch_scc0 .LBB0_2314
;   DI u32x2 pack(int, int, float a, float b, float c, float d, float&) const { u32x2 v; v.x = pack2(a, b); v.y = pack2(c, d); return v; }
; template <class ARow, class Epi>
; DI void gemm_tile(const ARow& arow, long a_kstride, const u16* __restrict__ Bt, long ldb, int K, int m0, int n0,
;                   const Epi& epi, char* smem) {
;     ...
;     for (int ks = 0; ks < 2; ++ks) {
;       bf16x8 wf[4], af[4];
; #pragma unroll
;       for (int j = 0; j < 4; ++j) {
;         wf[j] = *(const bf16x8*)(sb + j * 2048 + foff[ks]);
;         af[j] = *(const bf16x8*)(sa + j * 2048 + foff[ks]);
;       }
; #pragma unroll
;       for (int ni = 0; ni < 4; ++ni)
; #pragma unroll
;         for (int mi = 0; mi < 4; ++mi) acc[ni][mi] = __builtin_amdgcn_mfma_f32_16x16x32_bf16(wf[ni], af[mi], acc[ni][mi], 0, 0, 0);
;     }
;     asm volatile("s_waitcnt vmcnt(0)" ::: "memory");
;     __syncthreads();
;   }
;     ...
;   const int nh = n0 + wn * 64;
;   if (epi.packed(nh)) {
; #pragma unroll
;     for (int mi = 0; mi < 4; ++mi) {
;       const int m = m0 + wm * 64 + mi * 16 + fr;
;       float ss = 0.f;
;       u32x2 pk[4];
; #pragma unroll
;       for (int ni = 0; ni < 4; ++ni) pk[ni] = epi.pack(m, nh + ni * 16 + fq * 4, acc[ni][mi][0], acc[ni][mi][1], acc[ni][mi][2], acc[ni][mi][3], ss);
;       epi.finish16(m, nh, ss);
;       u16* rp = epi.rowp(m) + nh;
; #pragma unroll
;       for (int pp = 0; pp < 2; ++pp) {
;         u32x2 a = pk[2 * pp], b = pk[2 * pp + 1];
;         const u32x2 rx = __builtin_amdgcn_permlane16_swap(a.x, b.x, false, false);
;         const u32x2 ry = __builtin_amdgcn_permlane16_swap(a.y, b.y, false, false);
;         const int nst = (fq & 1) ? ((2 * pp + 1) * 16 + (fq - 1) * 4) : ((2 * pp) * 16 + fq * 4);
;         *(u32x4*)(rp + nst) = (u32x4){rx[0], ry[0], rx[1], ry[1]};
;       }
	v_add_u32_e32 v106, v89, v87
	ds_read_b128 v[66:69], v106 offset:49152
	v_add_u32_e32 v87, v88, v87
	ds_read_b128 v[70:73], v87 offset:32768
	ds_read_b128 v[74:77], v87 offset:34816
	ds_read_b128 v[78:81], v87 offset:36864
	ds_read_b128 v[90:93], v87 offset:38912
	v_add_u32_e32 v114, v89, v86
	s_waitcnt lgkmcnt(3)
	v_mfma_f32_16x16x32_bf16 v[60:63], v[66:69], v[70:73], v[60:63]
	s_waitcnt lgkmcnt(2)
	v_mfma_f32_16x16x32_bf16 v[56:59], v[66:69], v[74:77], v[56:59]
	s_waitcnt lgkmcnt(1)
	v_mfma_f32_16x16x32_bf16 v[48:51], v[66:69], v[78:81], v[48:51]
	s_waitcnt lgkmcnt(0)
	v_mfma_f32_16x16x32_bf16 v[40:43], v[66:69], v[90:93], v[40:43]
	ds_read_b128 v[66:69], v106 offset:51200
	s_waitcnt lgkmcnt(0)
	v_mfma_f32_16x16x32_bf16 v[36:39], v[66:69], v[70:73], v[36:39]
	v_mfma_f32_16x16x32_bf16 v[32:35], v[66:69], v[74:77], v[32:35]
	v_mfma_f32_16x16x32_bf16 v[94:97], v[66:69], v[78:81], v[28:31]
	v_mfma_f32_16x16x32_bf16 v[66:69], v[66:69], v[90:93], v[24:27]
	s_nop 2
	ds_read_b128 v[24:27], v106 offset:53248
	s_waitcnt lgkmcnt(0)
	v_mfma_f32_16x16x32_bf16 v[102:105], v[24:27], v[90:93], v[8:11]
	s_nop 2
	ds_read_b128 v[8:11], v106 offset:55296
	v_mfma_f32_16x16x32_bf16 v[20:23], v[24:27], v[70:73], v[20:23]
	s_waitcnt lgkmcnt(0)
	v_mfma_f32_16x16x32_bf16 v[70:73], v[8:11], v[70:73], v[4:7]
	s_nop 2
	ds_read_b128 v[4:7], v114 offset:49152
	v_mfma_f32_16x16x32_bf16 v[98:101], v[24:27], v[78:81], v[12:15]
	s_nop 2
	v_add_u32_e32 v12, v88, v86
	v_mfma_f32_16x16x32_bf16 v[16:19], v[24:27], v[74:77], v[16:19]
	ds_read_b128 v[86:89], v12 offset:32768
	ds_read_b128 v[106:109], v12 offset:36864
	ds_read_b128 v[110:113], v12 offset:38912
	v_mfma_f32_16x16x32_bf16 v[0:3], v[8:11], v[74:77], v[0:3]
	v_mfma_f32_16x16x32_bf16 v[74:77], v[8:11], v[78:81], v[52:55]
	v_mfma_f32_16x16x32_bf16 v[78:81], v[8:11], v[90:93], v[44:47]
	ds_read_b128 v[90:93], v12 offset:34816
	s_waitcnt lgkmcnt(3)
	v_mfma_f32_16x16x32_bf16 v[60:63], v[4:7], v[86:89], v[60:63]
	s_waitcnt lgkmcnt(0)
	v_mfma_f32_16x16x32_bf16 v[44:47], v[4:7], v[90:93], v[56:59]
	v_mfma_f32_16x16x32_bf16 v[28:31], v[4:7], v[106:109], v[48:51]
	v_mfma_f32_16x16x32_bf16 v[12:15], v[4:7], v[110:113], v[40:43]
	ds_read_b128 v[4:7], v114 offset:51200
	s_waitcnt lgkmcnt(0)
	v_mfma_f32_16x16x32_bf16 v[56:59], v[4:7], v[86:89], v[36:39]
	v_mfma_f32_16x16x32_bf16 v[40:43], v[4:7], v[90:93], v[32:35]
	v_mfma_f32_16x16x32_bf16 v[24:27], v[4:7], v[106:109], v[94:97]
	v_mfma_f32_16x16x32_bf16 v[8:11], v[4:7], v[110:113], v[66:69]
	ds_read_b128 v[4:7], v114 offset:53248
	s_nop 0
	ds_read_b128 v[94:97], v114 offset:55296
	s_waitcnt lgkmcnt(0)
	s_waitcnt vmcnt(0)
	s_waitcnt lgkmcnt(0)
	v_mfma_f32_16x16x32_bf16 v[32:35], v[94:97], v[90:93], v[0:3]
	s_nop 2
	v_or_b32_e32 v0, s0, v64
	v_lshl_add_u32 v66, v85, 6, v0
	v_lshl_or_b32 v68, v84, 6, s34
	v_mfma_f32_16x16x32_bf16 v[52:55], v[4:7], v[86:89], v[20:23]
	v_cmp_lt_i32_e32 vcc, s30, v68
	s_barrier
	v_mfma_f32_16x16x32_bf16 v[36:39], v[4:7], v[90:93], v[16:19]
	v_mfma_f32_16x16x32_bf16 v[20:23], v[4:7], v[106:109], v[98:101]
	v_mfma_f32_16x16x32_bf16 v[4:7], v[4:7], v[110:113], v[102:105]
	v_mfma_f32_16x16x32_bf16 v[48:51], v[94:97], v[86:89], v[70:73]
	v_mfma_f32_16x16x32_bf16 v[16:19], v[94:97], v[106:109], v[74:77]
	s_nop 1
	v_lshlrev_b32_e32 v70, 2, v83
	v_or_b32_e32 v64, v68, v70
	v_mfma_f32_16x16x32_bf16 v[0:3], v[94:97], v[110:113], v[78:81]
	s_nop 7
	v_readfirstlane_b32 s99, v68
	s_cmpk_ge_u32 s99, 0x400
	s_cbranch_scc0 .Lfe_D_not_plain
	s_cmpk_lt_u32 s99, 0xc00
	s_cbranch_scc0 .Lfe_D_not_plain
	s_load_dwordx2 s[100:101], s[56:57], 0x130
	v_and_b32_e32 v152, 1, v83
	v_mul_u32_u24_e32 v152, 12, v152
	v_lshl_add_u32 v152, v83, 2, v152
	v_add_u32_e32 v152, v152, v68
	v_lshl_add_u32 v152, v66, 12, v152
	v_lshlrev_b32_e32 v152, 1, v152
	v_add_u32_e32 v153, 0x20000, v152
	v_add_u32_e32 v154, 0x40000, v152
	v_add_u32_e32 v155, 0x60000, v152
	s_nop 3
	v_cvt_pk_bf16_f32 v120, v60, v61
	v_cvt_pk_bf16_f32 v121, v62, v63
	v_cvt_pk_bf16_f32 v122, v56, v57
	v_cvt_pk_bf16_f32 v123, v58, v59
	v_cvt_pk_bf16_f32 v124, v52, v53
	v_cvt_pk_bf16_f32 v125, v54, v55
	v_cvt_pk_bf16_f32 v126, v48, v49
	v_cvt_pk_bf16_f32 v127, v50, v51
	s_nop 1
	v_permlane16_swap_b32_e32 v120, v122
	v_permlane16_swap_b32_e32 v121, v123
	v_permlane16_swap_b32_e32 v124, v126
	v_permlane16_swap_b32_e32 v125, v127
	s_waitcnt lgkmcnt(0)
	global_store_dwordx4 v152, v[120:123], s[100:101]
	global_store_dwordx4 v152, v[124:127], s[100:101] offset:64
	v_cvt_pk_bf16_f32 v128, v44, v45
	v_cvt_pk_bf16_f32 v129, v46, v47
	v_cvt_pk_bf16_f32 v130, v40, v41
	v_cvt_pk_bf16_f32 v131, v42, v43
	v_cvt_pk_bf16_f32 v132, v36, v37
	v_cvt_pk_bf16_f32 v133, v38, v39
	v_cvt_pk_bf16_f32 v134, v32, v33
	v_cvt_pk_bf16_f32 v135, v34, v35
	s_nop 1
	v_permlane16_swap_b32_e32 v128, v130
	v_permlane16_swap_b32_e32 v129, v131
	v_permlane16_swap_b32_e32 v132, v134
	v_permlane16_swap_b32_e32 v133, v135
	global_store_dwordx4 v153, v[128:131], s[100:101]
	global_store_dwordx4 v153, v[132:135], s[100:101] offset:64
	v_cvt_pk_bf16_f32 v136, v28, v29
	v_cvt_pk_bf16_f32 v137, v30, v31
	v_cvt_pk_bf16_f32 v138, v24, v25
	v_cvt_pk_bf16_f32 v139, v26, v27
	v_cvt_pk_bf16_f32 v140, v20, v21
	v_cvt_pk_bf16_f32 v141, v22, v23
	v_cvt_pk_bf16_f32 v142, v16, v17
	v_cvt_pk_bf16_f32 v143, v18, v19
	s_nop 1
	v_permlane16_swap_b32_e32 v136, v138
	v_permlane16_swap_b32_e32 v137, v139
	v_permlane16_swap_b32_e32 v140, v142
	v_permlane16_swap_b32_e32 v141, v143
	global_store_dwordx4 v154, v[136:139], s[100:101]
	global_store_dwordx4 v154, v[140:143], s[100:101] offset:64
	v_cvt_pk_bf16_f32 v144, v12, v13
	v_cvt_pk_bf16_f32 v145, v14, v15
	v_cvt_pk_bf16_f32 v146, v8, v9
	v_cvt_pk_bf16_f32 v147, v10, v11
	v_cvt_pk_bf16_f32 v148, v4, v5
	v_cvt_pk_bf16_f32 v149, v6, v7
	v_cvt_pk_bf16_f32 v150, v0, v1
	v_cvt_pk_bf16_f32 v151, v2, v3
	s_nop 1
	v_permlane16_swap_b32_e32 v144, v146
	v_permlane16_swap_b32_e32 v145, v147
	v_permlane16_swap_b32_e32 v148, v150
	v_permlane16_swap_b32_e32 v149, v151
	global_store_dwordx4 v155, v[144:147], s[100:101]
	global_store_dwordx4 v155, v[148:151], s[100:101] offset:64
	s_branch .Lfe_join_D
